# k01 + ssq rows of each GEMM unit prefetched to a double-buffered LDS stash by LDS-DMA; epilogue reads them with ds_read_b128 (7 phases)
# speedup vs baseline: 1.0099x; 1.0099x over previous
.LBB0_201:
	s_and_b32 s99, s45, 1
	s_lshl_b32 s99, s99, 12
	v_readfirstlane_b32 s100, v0
	s_and_b32 s100, s100, 0xc0
	s_lshl_b32 s100, s100, 4
	s_add_i32 s99, s99, s100
	s_add_i32 m0, s99, 0x21000
	s_lshl_b32 s99, s26, 12
	s_add_u32 s100, s76, s99
	s_addc_u32 s101, s77, 0
	v_and_b32_e32 v129, 0xff, v0
	v_lshlrev_b32_e32 v129, 4, v129
	global_load_lds_dwordx4 v129, s[100:101]
	s_ashr_i32 s21, s20, 31
	s_lshl_b64 s[0:1], s[20:21], 19
	s_add_u32 s22, s78, s0
	s_addc_u32 s23, s79, s1
	s_and_b64 s[0:1], s[4:5], exec
	s_cselect_b32 s21, s23, s29
	s_cselect_b32 s47, s22, s28
	s_ashr_i32 s19, s18, 31
	s_lshl_b64 s[0:1], s[18:19], 19
	s_add_u32 s24, s34, s0
	s_addc_u32 s25, s35, s1
	s_and_b64 s[0:1], s[4:5], exec
	s_cselect_b32 s19, s25, s3
	s_cselect_b32 s48, s24, s2
	s_add_u32 s28, s28, 0x40080
	s_addc_u32 s29, s29, 0
	s_add_u32 s49, s2, 0x100
	v_mov_b32_e32 v2, 0
	s_addc_u32 s50, s3, 0
	s_mov_b32 s51, -2
	v_mov_b32_e32 v3, v2
	v_mov_b32_e32 v4, v2
	v_mov_b32_e32 v5, v2
	v_mov_b32_e32 v6, v2
	v_mov_b32_e32 v7, v2
	v_mov_b32_e32 v8, v2
	v_mov_b32_e32 v9, v2
	v_mov_b32_e32 v18, v2
	v_mov_b32_e32 v19, v2
	v_mov_b32_e32 v20, v2
	v_mov_b32_e32 v21, v2
	v_mov_b32_e32 v22, v2
	v_mov_b32_e32 v23, v2
	v_mov_b32_e32 v24, v2
	v_mov_b32_e32 v25, v2
	v_mov_b32_e32 v34, v2
	v_mov_b32_e32 v35, v2
	v_mov_b32_e32 v36, v2
	v_mov_b32_e32 v37, v2
	v_mov_b32_e32 v38, v2
	v_mov_b32_e32 v39, v2
	v_mov_b32_e32 v40, v2
	v_mov_b32_e32 v41, v2
	v_mov_b32_e32 v50, v2
	v_mov_b32_e32 v51, v2
	v_mov_b32_e32 v52, v2
	v_mov_b32_e32 v53, v2
	v_mov_b32_e32 v54, v2
	v_mov_b32_e32 v55, v2
	v_mov_b32_e32 v56, v2
	v_mov_b32_e32 v57, v2
	v_mov_b32_e32 v10, v2
	v_mov_b32_e32 v11, v2
	v_mov_b32_e32 v12, v2
	v_mov_b32_e32 v13, v2
	v_mov_b32_e32 v14, v2
	v_mov_b32_e32 v15, v2
	v_mov_b32_e32 v16, v2
	v_mov_b32_e32 v17, v2
	v_mov_b32_e32 v26, v2
	v_mov_b32_e32 v27, v2
	v_mov_b32_e32 v28, v2
	v_mov_b32_e32 v29, v2
	v_mov_b32_e32 v30, v2
	v_mov_b32_e32 v31, v2
	v_mov_b32_e32 v32, v2
	v_mov_b32_e32 v33, v2
	v_mov_b32_e32 v42, v2
	v_mov_b32_e32 v43, v2
	v_mov_b32_e32 v44, v2
	v_mov_b32_e32 v45, v2
	v_mov_b32_e32 v46, v2
	v_mov_b32_e32 v47, v2
	v_mov_b32_e32 v48, v2
	v_mov_b32_e32 v49, v2
	v_mov_b32_e32 v58, v2
	v_mov_b32_e32 v59, v2
	v_mov_b32_e32 v60, v2
	v_mov_b32_e32 v61, v2
	v_mov_b32_e32 v62, v2
	v_mov_b32_e32 v63, v2
	v_mov_b32_e32 v64, v2
	v_mov_b32_e32 v65, v2
	v_mov_b32_e32 v66, v2
	v_mov_b32_e32 v67, v2
	v_mov_b32_e32 v68, v2
	v_mov_b32_e32 v69, v2
	v_mov_b32_e32 v70, v2
	v_mov_b32_e32 v71, v2
	v_mov_b32_e32 v72, v2
	v_mov_b32_e32 v73, v2
	v_mov_b32_e32 v82, v2
	v_mov_b32_e32 v83, v2
	v_mov_b32_e32 v84, v2
	v_mov_b32_e32 v85, v2
	v_mov_b32_e32 v86, v2
	v_mov_b32_e32 v87, v2
	v_mov_b32_e32 v88, v2
	v_mov_b32_e32 v89, v2
	v_mov_b32_e32 v98, v2
	v_mov_b32_e32 v99, v2
	v_mov_b32_e32 v100, v2
	v_mov_b32_e32 v101, v2
	v_mov_b32_e32 v102, v2
	v_mov_b32_e32 v103, v2
	v_mov_b32_e32 v104, v2
	v_mov_b32_e32 v105, v2
	v_mov_b32_e32 v114, v2
	v_mov_b32_e32 v115, v2
	v_mov_b32_e32 v116, v2
	v_mov_b32_e32 v117, v2
	v_mov_b32_e32 v122, v2
	v_mov_b32_e32 v123, v2
	v_mov_b32_e32 v124, v2
	v_mov_b32_e32 v125, v2
	v_mov_b32_e32 v74, v2
	v_mov_b32_e32 v75, v2
	v_mov_b32_e32 v76, v2
	v_mov_b32_e32 v77, v2
	v_mov_b32_e32 v78, v2
	v_mov_b32_e32 v79, v2
	v_mov_b32_e32 v80, v2
	v_mov_b32_e32 v81, v2
	v_mov_b32_e32 v90, v2
	v_mov_b32_e32 v91, v2
	v_mov_b32_e32 v92, v2
	v_mov_b32_e32 v93, v2
	v_mov_b32_e32 v94, v2
	v_mov_b32_e32 v95, v2
	v_mov_b32_e32 v96, v2
	v_mov_b32_e32 v97, v2
	v_mov_b32_e32 v106, v2
	v_mov_b32_e32 v107, v2
	v_mov_b32_e32 v108, v2
	v_mov_b32_e32 v109, v2
	v_mov_b32_e32 v110, v2
	v_mov_b32_e32 v111, v2
	v_mov_b32_e32 v112, v2
	v_mov_b32_e32 v113, v2
	v_mov_b32_e32 v118, v2
	v_mov_b32_e32 v119, v2
	v_mov_b32_e32 v120, v2
	v_mov_b32_e32 v121, v2
	v_mov_b32_e32 v126, v2
	v_mov_b32_e32 v127, v2
	v_mov_b32_e32 v128, v2
	v_mov_b32_e32 v129, v2

.LBB0_205:
	v_lshl_add_u32 v162, s26, 8, v165
	s_and_b32 s99, s45, 1
	s_lshl_b32 s99, s99, 12
	s_add_i32 s99, s99, 0x21000
	v_lshl_add_u32 v252, v165, 4, s99
	v_ashrrev_i32_e32 v163, 31, v162
	v_lshl_add_u64 v[148:149], v[162:163], 4, s[76:77]
	ds_read_b128 v[172:175], v252
	v_or_b32_e32 v160, 16, v162
	v_ashrrev_i32_e32 v161, 31, v160
	v_lshl_add_u64 v[148:149], v[160:161], 4, s[76:77]
	ds_read_b128 v[176:179], v252 offset:256
	v_or_b32_e32 v158, 32, v162
	v_ashrrev_i32_e32 v159, 31, v158
	v_lshl_add_u64 v[148:149], v[158:159], 4, s[76:77]
	ds_read_b128 v[180:183], v252 offset:512
	v_or_b32_e32 v156, 48, v162
	v_ashrrev_i32_e32 v157, 31, v156
	v_lshl_add_u64 v[148:149], v[156:157], 4, s[76:77]
	ds_read_b128 v[184:187], v252 offset:768
	v_add_u32_e32 v154, 0x80, v162
	v_ashrrev_i32_e32 v155, 31, v154
	v_lshl_add_u64 v[148:149], v[154:155], 4, s[76:77]
	ds_read_b128 v[188:191], v252 offset:2048
	v_add_u32_e32 v152, 0x90, v162
	v_ashrrev_i32_e32 v153, 31, v152
	v_lshl_add_u64 v[148:149], v[152:153], 4, s[76:77]
	ds_read_b128 v[192:195], v252 offset:2304
	v_add_u32_e32 v150, 0xa0, v162
	v_ashrrev_i32_e32 v151, 31, v150
	v_lshl_add_u64 v[148:149], v[150:151], 4, s[76:77]
	ds_read_b128 v[196:199], v252 offset:2560
	v_add_u32_e32 v148, 0xb0, v162
	v_ashrrev_i32_e32 v149, 31, v148
	v_lshl_add_u64 v[200:201], v[148:149], 4, s[76:77]
	ds_read_b128 v[200:203], v252 offset:2816
	v_pk_mul_f32 v[116:117], v[120:121], v[116:117]
	v_pk_mul_f32 v[114:115], v[118:119], v[114:115]
	s_lshl_b32 s0, s46, 7
	s_ashr_i32 s1, s0, 31
	s_lshl_b64 s[2:3], s[0:1], 1
	v_pk_mul_f32 v[122:123], v[126:127], v[122:123]
	v_pk_mul_f32 v[124:125], v[128:129], v[124:125]
	v_pk_mul_f32 v[100:101], v[108:109], v[100:101]
	v_pk_mul_f32 v[98:99], v[106:107], v[98:99]
	v_pk_mul_f32 v[102:103], v[110:111], v[102:103]
	v_pk_mul_f32 v[104:105], v[112:113], v[104:105]
	v_pk_mul_f32 v[84:85], v[92:93], v[84:85]
	v_pk_mul_f32 v[82:83], v[90:91], v[82:83]
	v_pk_mul_f32 v[86:87], v[94:95], v[86:87]
	v_pk_mul_f32 v[88:89], v[96:97], v[88:89]
	v_pk_mul_f32 v[68:69], v[76:77], v[68:69]
	v_pk_mul_f32 v[66:67], v[74:75], v[66:67]
	v_pk_mul_f32 v[70:71], v[78:79], v[70:71]
	v_pk_mul_f32 v[72:73], v[80:81], v[72:73]
	v_pk_mul_f32 v[52:53], v[60:61], v[52:53]
	v_pk_mul_f32 v[50:51], v[58:59], v[50:51]
	v_pk_mul_f32 v[54:55], v[62:63], v[54:55]
	v_pk_mul_f32 v[56:57], v[64:65], v[56:57]
	v_pk_mul_f32 v[36:37], v[44:45], v[36:37]
	v_pk_mul_f32 v[34:35], v[42:43], v[34:35]
	v_pk_mul_f32 v[38:39], v[46:47], v[38:39]
	v_pk_mul_f32 v[40:41], v[48:49], v[40:41]
	v_pk_mul_f32 v[20:21], v[28:29], v[20:21]
	v_pk_mul_f32 v[18:19], v[26:27], v[18:19]
	v_pk_mul_f32 v[22:23], v[30:31], v[22:23]
	v_pk_mul_f32 v[24:25], v[32:33], v[24:25]
	v_pk_mul_f32 v[4:5], v[12:13], v[4:5]
	v_pk_mul_f32 v[2:3], v[10:11], v[2:3]
	v_pk_mul_f32 v[8:9], v[16:17], v[8:9]
	v_pk_mul_f32 v[6:7], v[14:15], v[6:7]
	s_andn2_b64 vcc, exec, s[4:5]
	s_waitcnt lgkmcnt(0)
	v_mov_b32_e32 v204, v173
	v_mov_b32_e32 v205, v174
	v_mov_b32_e32 v173, v175
	v_pk_add_f32 v[172:173], v[204:205], v[172:173]
	s_nop 0
	v_add_f32_e32 v164, v172, v173
	v_fmamk_f32 v164, v164, 0x3a800000, v170
	v_rsq_f32_e32 v164, v164
	v_mov_b32_e32 v172, v177
	v_mov_b32_e32 v173, v178
	v_mov_b32_e32 v177, v179
	v_pk_add_f32 v[172:173], v[172:173], v[176:177]
	v_mul_f32_e32 v164, v164, v164
	v_add_f32_e32 v171, v172, v173
	v_fmamk_f32 v171, v171, 0x3a800000, v170
	v_pk_mul_f32 v[118:119], v[116:117], v[164:165] op_sel_hi:[1,0]
	v_pk_mul_f32 v[116:117], v[114:115], v[164:165] op_sel_hi:[1,0]
	v_lshlrev_b64 v[114:115], 11, v[162:163]
	v_rsq_f32_e32 v178, v171
	v_lshl_add_u64 v[114:115], s[12:13], 0, v[114:115]
	v_lshl_add_u64 v[114:115], v[114:115], 0, s[2:3]
	v_mov_b32_e32 v172, v181
	v_mov_b32_e32 v173, v182
	v_mov_b32_e32 v181, v183
	v_lshl_add_u64 v[114:115], v[114:115], 0, s[8:9]
	v_pk_add_f32 v[172:173], v[172:173], v[180:181]
	v_pk_mul_f32 v[122:123], v[122:123], v[164:165] op_sel_hi:[1,0]
	v_lshl_add_u64 v[120:121], v[114:115], 0, v[138:139]
	v_cvt_pk_bf16_f32 v114, v122, v123
	v_add_f32_e32 v171, v172, v173
	v_pk_mul_f32 v[124:125], v[124:125], v[164:165] op_sel_hi:[1,0]
	v_fmamk_f32 v171, v171, 0x3a800000, v170
	v_cvt_pk_bf16_f32 v115, v124, v125
	v_cvt_pk_bf16_f32 v116, v116, v117
	v_cvt_pk_bf16_f32 v117, v118, v119
	global_store_dwordx4 v[120:121], v[114:117], off
	v_rsq_f32_e32 v179, v171
	v_mov_b32_e32 v172, v185
	v_mul_f32_e32 v114, v178, v178
	v_pk_mul_f32 v[106:107], v[100:101], v[114:115] op_sel_hi:[1,0]
	v_pk_mul_f32 v[100:101], v[98:99], v[114:115] op_sel_hi:[1,0]
	v_lshlrev_b64 v[98:99], 11, v[160:161]
	v_lshl_add_u64 v[98:99], s[12:13], 0, v[98:99]
	v_lshl_add_u64 v[98:99], v[98:99], 0, s[2:3]
	v_mov_b32_e32 v173, v186
	v_mov_b32_e32 v185, v187
	v_lshl_add_u64 v[98:99], v[98:99], 0, s[8:9]
	v_pk_add_f32 v[172:173], v[172:173], v[184:185]
	v_pk_mul_f32 v[102:103], v[102:103], v[114:115] op_sel_hi:[1,0]
	v_lshl_add_u64 v[108:109], v[98:99], 0, v[138:139]
	v_cvt_pk_bf16_f32 v98, v102, v103
	v_add_f32_e32 v171, v172, v173
	v_pk_mul_f32 v[104:105], v[104:105], v[114:115] op_sel_hi:[1,0]
	v_fmamk_f32 v171, v171, 0x3a800000, v170
	v_cvt_pk_bf16_f32 v99, v104, v105
	v_cvt_pk_bf16_f32 v100, v100, v101
	v_cvt_pk_bf16_f32 v101, v106, v107
	global_store_dwordx4 v[108:109], v[98:101], off
	v_rsq_f32_e32 v175, v171
	v_mov_b32_e32 v172, v189
	v_mul_f32_e32 v98, v179, v179
	v_pk_mul_f32 v[90:91], v[84:85], v[98:99] op_sel_hi:[1,0]
	v_pk_mul_f32 v[84:85], v[82:83], v[98:99] op_sel_hi:[1,0]
	v_lshlrev_b64 v[82:83], 11, v[158:159]
	v_lshl_add_u64 v[82:83], s[12:13], 0, v[82:83]
	v_lshl_add_u64 v[82:83], v[82:83], 0, s[2:3]
	v_mov_b32_e32 v173, v190
	v_mov_b32_e32 v189, v191
	v_lshl_add_u64 v[82:83], v[82:83], 0, s[8:9]
	v_pk_add_f32 v[172:173], v[172:173], v[188:189]
	v_pk_mul_f32 v[86:87], v[86:87], v[98:99] op_sel_hi:[1,0]
	v_lshl_add_u64 v[92:93], v[82:83], 0, v[138:139]
	v_cvt_pk_bf16_f32 v82, v86, v87
	v_add_f32_e32 v171, v172, v173
	v_pk_mul_f32 v[88:89], v[88:89], v[98:99] op_sel_hi:[1,0]
	v_fmamk_f32 v171, v171, 0x3a800000, v170
	v_cvt_pk_bf16_f32 v83, v88, v89
	v_cvt_pk_bf16_f32 v84, v84, v85
	v_cvt_pk_bf16_f32 v85, v90, v91
	global_store_dwordx4 v[92:93], v[82:85], off
	v_rsq_f32_e32 v174, v171
	v_mov_b32_e32 v172, v193
	v_mul_f32_e32 v82, v175, v175
	v_pk_mul_f32 v[74:75], v[68:69], v[82:83] op_sel_hi:[1,0]
	v_pk_mul_f32 v[68:69], v[66:67], v[82:83] op_sel_hi:[1,0]
	v_lshlrev_b64 v[66:67], 11, v[156:157]
	v_lshl_add_u64 v[66:67], s[12:13], 0, v[66:67]
	v_lshl_add_u64 v[66:67], v[66:67], 0, s[2:3]
	v_mov_b32_e32 v173, v194
	v_mov_b32_e32 v193, v195
	v_lshl_add_u64 v[66:67], v[66:67], 0, s[8:9]
	v_pk_add_f32 v[172:173], v[172:173], v[192:193]
	v_pk_mul_f32 v[70:71], v[70:71], v[82:83] op_sel_hi:[1,0]
	v_lshl_add_u64 v[76:77], v[66:67], 0, v[138:139]
	v_cvt_pk_bf16_f32 v66, v70, v71
	v_add_f32_e32 v171, v172, v173
	v_pk_mul_f32 v[72:73], v[72:73], v[82:83] op_sel_hi:[1,0]
	v_fmamk_f32 v171, v171, 0x3a800000, v170
	v_cvt_pk_bf16_f32 v67, v72, v73
	v_cvt_pk_bf16_f32 v68, v68, v69
	v_cvt_pk_bf16_f32 v69, v74, v75
	global_store_dwordx4 v[76:77], v[66:69], off
	v_rsq_f32_e32 v173, v171
	v_mov_b32_e32 v176, v197
	v_mul_f32_e32 v66, v174, v174
	v_pk_mul_f32 v[58:59], v[52:53], v[66:67] op_sel_hi:[1,0]
	v_pk_mul_f32 v[52:53], v[50:51], v[66:67] op_sel_hi:[1,0]
	v_lshlrev_b64 v[50:51], 11, v[154:155]
	v_lshl_add_u64 v[50:51], s[12:13], 0, v[50:51]
	v_lshl_add_u64 v[50:51], v[50:51], 0, s[2:3]
	v_mov_b32_e32 v177, v198
	v_mov_b32_e32 v197, v199
	v_lshl_add_u64 v[50:51], v[50:51], 0, s[8:9]
	v_pk_add_f32 v[176:177], v[176:177], v[196:197]
	v_pk_mul_f32 v[54:55], v[54:55], v[66:67] op_sel_hi:[1,0]
	v_lshl_add_u64 v[60:61], v[50:51], 0, v[138:139]
	v_cvt_pk_bf16_f32 v50, v54, v55
	v_add_f32_e32 v171, v176, v177
	v_pk_mul_f32 v[56:57], v[56:57], v[66:67] op_sel_hi:[1,0]
	v_fmamk_f32 v171, v171, 0x3a800000, v170
	v_cvt_pk_bf16_f32 v51, v56, v57
	v_cvt_pk_bf16_f32 v52, v52, v53
	v_cvt_pk_bf16_f32 v53, v58, v59
	global_store_dwordx4 v[60:61], v[50:53], off
	v_rsq_f32_e32 v172, v171
	v_mov_b32_e32 v176, v201
	v_mul_f32_e32 v50, v173, v173
	v_pk_mul_f32 v[42:43], v[36:37], v[50:51] op_sel_hi:[1,0]
	v_pk_mul_f32 v[36:37], v[34:35], v[50:51] op_sel_hi:[1,0]
	v_lshlrev_b64 v[34:35], 11, v[152:153]
	v_lshl_add_u64 v[34:35], s[12:13], 0, v[34:35]
	v_lshl_add_u64 v[34:35], v[34:35], 0, s[2:3]
	v_mov_b32_e32 v177, v202
	v_mov_b32_e32 v201, v203
	v_lshl_add_u64 v[34:35], v[34:35], 0, s[8:9]
	v_pk_add_f32 v[176:177], v[176:177], v[200:201]
	v_pk_mul_f32 v[38:39], v[38:39], v[50:51] op_sel_hi:[1,0]
	v_lshl_add_u64 v[44:45], v[34:35], 0, v[138:139]
	v_cvt_pk_bf16_f32 v34, v38, v39
	v_add_f32_e32 v171, v176, v177
	v_pk_mul_f32 v[40:41], v[40:41], v[50:51] op_sel_hi:[1,0]
	v_fmamk_f32 v171, v171, 0x3a800000, v170
	v_cvt_pk_bf16_f32 v35, v40, v41
	v_cvt_pk_bf16_f32 v36, v36, v37
	v_cvt_pk_bf16_f32 v37, v42, v43
	global_store_dwordx4 v[44:45], v[34:37], off
	v_rsq_f32_e32 v171, v171
	s_nop 0
	v_mul_f32_e32 v34, v172, v172
	v_pk_mul_f32 v[26:27], v[20:21], v[34:35] op_sel_hi:[1,0]
	v_pk_mul_f32 v[20:21], v[18:19], v[34:35] op_sel_hi:[1,0]
	v_lshlrev_b64 v[18:19], 11, v[150:151]
	v_lshl_add_u64 v[18:19], s[12:13], 0, v[18:19]
	v_lshl_add_u64 v[18:19], v[18:19], 0, s[2:3]
	v_lshl_add_u64 v[18:19], v[18:19], 0, s[8:9]
	v_pk_mul_f32 v[22:23], v[22:23], v[34:35] op_sel_hi:[1,0]
	v_lshl_add_u64 v[28:29], v[18:19], 0, v[138:139]
	v_cvt_pk_bf16_f32 v18, v22, v23
	v_pk_mul_f32 v[24:25], v[24:25], v[34:35] op_sel_hi:[1,0]
	s_nop 0
	v_cvt_pk_bf16_f32 v19, v24, v25
	v_cvt_pk_bf16_f32 v20, v20, v21
	v_cvt_pk_bf16_f32 v21, v26, v27
	global_store_dwordx4 v[28:29], v[18:21], off
	s_nop 1
	v_mul_f32_e32 v18, v171, v171
	v_pk_mul_f32 v[10:11], v[4:5], v[18:19] op_sel_hi:[1,0]
	v_pk_mul_f32 v[4:5], v[2:3], v[18:19] op_sel_hi:[1,0]
	v_lshlrev_b64 v[2:3], 11, v[148:149]
	v_lshl_add_u64 v[2:3], s[12:13], 0, v[2:3]
	v_lshl_add_u64 v[2:3], v[2:3], 0, s[2:3]
	v_lshl_add_u64 v[2:3], v[2:3], 0, s[8:9]
	v_lshl_add_u64 v[12:13], v[2:3], 0, v[138:139]
	s_mov_b64 s[2:3], -1
	v_pk_mul_f32 v[8:9], v[8:9], v[18:19] op_sel_hi:[1,0]
	v_pk_mul_f32 v[6:7], v[6:7], v[18:19] op_sel_hi:[1,0]
	s_nop 0
	v_cvt_pk_bf16_f32 v2, v6, v7
	v_cvt_pk_bf16_f32 v3, v8, v9
	v_cvt_pk_bf16_f32 v4, v4, v5
	v_cvt_pk_bf16_f32 v5, v10, v11
	global_store_dwordx4 v[12:13], v[2:5], off
	s_cbranch_vccnz .LBB0_194
	s_andn2_b64 vcc, exec, s[10:11]
	s_cbranch_vccnz .LBB0_193
	s_barrier
	s_branch .LBB0_193

.LBB0_470:
	s_and_b32 s99, s48, 1
	s_lshl_b32 s99, s99, 12
	v_readfirstlane_b32 s100, v0
	s_and_b32 s100, s100, 0xc0
	s_lshl_b32 s100, s100, 4
	s_add_i32 s99, s99, s100
	s_add_i32 m0, s99, 0x21000
	s_lshl_b32 s99, s26, 12
	s_add_u32 s100, s76, s99
	s_addc_u32 s101, s77, 0
	v_and_b32_e32 v129, 0xff, v0
	v_lshlrev_b32_e32 v129, 4, v129
	global_load_lds_dwordx4 v129, s[100:101]
	s_ashr_i32 s21, s20, 31
	s_lshl_b64 s[0:1], s[20:21], 19
	s_add_u32 s22, s78, s0
	s_addc_u32 s23, s79, s1
	s_and_b64 s[0:1], s[4:5], exec
	s_cselect_b32 s21, s23, s29
	s_cselect_b32 s49, s22, s28
	s_ashr_i32 s19, s18, 31
	s_lshl_b64 s[0:1], s[18:19], 19
	s_add_u32 s24, s33, s0
	s_addc_u32 s25, s34, s1
	s_and_b64 s[0:1], s[4:5], exec
	s_cselect_b32 s19, s25, s3
	s_cselect_b32 s50, s24, s2
	s_add_u32 s28, s28, 0x40080
	s_addc_u32 s29, s29, 0
	s_add_u32 s51, s2, 0x100
	v_mov_b32_e32 v2, 0
	s_addc_u32 s52, s3, 0
	s_mov_b32 s53, -2
	v_mov_b32_e32 v3, v2
	v_mov_b32_e32 v4, v2
	v_mov_b32_e32 v5, v2
	v_mov_b32_e32 v10, v2
	v_mov_b32_e32 v11, v2
	v_mov_b32_e32 v12, v2
	v_mov_b32_e32 v13, v2
	v_mov_b32_e32 v18, v2
	v_mov_b32_e32 v19, v2
	v_mov_b32_e32 v20, v2
	v_mov_b32_e32 v21, v2
	v_mov_b32_e32 v26, v2
	v_mov_b32_e32 v27, v2
	v_mov_b32_e32 v28, v2
	v_mov_b32_e32 v29, v2
	v_mov_b32_e32 v34, v2
	v_mov_b32_e32 v35, v2
	v_mov_b32_e32 v36, v2
	v_mov_b32_e32 v37, v2
	v_mov_b32_e32 v42, v2
	v_mov_b32_e32 v43, v2
	v_mov_b32_e32 v44, v2
	v_mov_b32_e32 v45, v2
	v_mov_b32_e32 v50, v2
	v_mov_b32_e32 v51, v2
	v_mov_b32_e32 v52, v2
	v_mov_b32_e32 v53, v2
	v_mov_b32_e32 v58, v2
	v_mov_b32_e32 v59, v2
	v_mov_b32_e32 v60, v2
	v_mov_b32_e32 v61, v2
	v_mov_b32_e32 v6, v2
	v_mov_b32_e32 v7, v2
	v_mov_b32_e32 v8, v2
	v_mov_b32_e32 v9, v2
	v_mov_b32_e32 v14, v2
	v_mov_b32_e32 v15, v2
	v_mov_b32_e32 v16, v2
	v_mov_b32_e32 v17, v2
	v_mov_b32_e32 v22, v2
	v_mov_b32_e32 v23, v2
	v_mov_b32_e32 v24, v2
	v_mov_b32_e32 v25, v2
	v_mov_b32_e32 v30, v2
	v_mov_b32_e32 v31, v2
	v_mov_b32_e32 v32, v2
	v_mov_b32_e32 v33, v2
	v_mov_b32_e32 v38, v2
	v_mov_b32_e32 v39, v2
	v_mov_b32_e32 v40, v2
	v_mov_b32_e32 v41, v2
	v_mov_b32_e32 v46, v2
	v_mov_b32_e32 v47, v2
	v_mov_b32_e32 v48, v2
	v_mov_b32_e32 v49, v2
	v_mov_b32_e32 v54, v2
	v_mov_b32_e32 v55, v2
	v_mov_b32_e32 v56, v2
	v_mov_b32_e32 v57, v2
	v_mov_b32_e32 v62, v2
	v_mov_b32_e32 v63, v2
	v_mov_b32_e32 v64, v2
	v_mov_b32_e32 v65, v2
	v_mov_b32_e32 v66, v2
	v_mov_b32_e32 v67, v2
	v_mov_b32_e32 v68, v2
	v_mov_b32_e32 v69, v2
	v_mov_b32_e32 v74, v2
	v_mov_b32_e32 v75, v2
	v_mov_b32_e32 v76, v2
	v_mov_b32_e32 v77, v2
	v_mov_b32_e32 v82, v2
	v_mov_b32_e32 v83, v2
	v_mov_b32_e32 v84, v2
	v_mov_b32_e32 v85, v2
	v_mov_b32_e32 v90, v2
	v_mov_b32_e32 v91, v2
	v_mov_b32_e32 v92, v2
	v_mov_b32_e32 v93, v2
	v_mov_b32_e32 v98, v2
	v_mov_b32_e32 v99, v2
	v_mov_b32_e32 v100, v2
	v_mov_b32_e32 v101, v2
	v_mov_b32_e32 v106, v2
	v_mov_b32_e32 v107, v2
	v_mov_b32_e32 v108, v2
	v_mov_b32_e32 v109, v2
	v_mov_b32_e32 v114, v2
	v_mov_b32_e32 v115, v2
	v_mov_b32_e32 v116, v2
	v_mov_b32_e32 v117, v2
	v_mov_b32_e32 v122, v2
	v_mov_b32_e32 v123, v2
	v_mov_b32_e32 v124, v2
	v_mov_b32_e32 v125, v2
	v_mov_b32_e32 v70, v2
	v_mov_b32_e32 v71, v2
	v_mov_b32_e32 v72, v2
	v_mov_b32_e32 v73, v2
	v_mov_b32_e32 v78, v2
	v_mov_b32_e32 v79, v2
	v_mov_b32_e32 v80, v2
	v_mov_b32_e32 v81, v2
	v_mov_b32_e32 v86, v2
	v_mov_b32_e32 v87, v2
	v_mov_b32_e32 v88, v2
	v_mov_b32_e32 v89, v2
	v_mov_b32_e32 v94, v2
	v_mov_b32_e32 v95, v2
	v_mov_b32_e32 v96, v2
	v_mov_b32_e32 v97, v2
	v_mov_b32_e32 v102, v2
	v_mov_b32_e32 v103, v2
	v_mov_b32_e32 v104, v2
	v_mov_b32_e32 v105, v2
	v_mov_b32_e32 v110, v2
	v_mov_b32_e32 v111, v2
	v_mov_b32_e32 v112, v2
	v_mov_b32_e32 v113, v2
	v_mov_b32_e32 v118, v2
	v_mov_b32_e32 v119, v2
	v_mov_b32_e32 v120, v2
	v_mov_b32_e32 v121, v2
	v_mov_b32_e32 v126, v2
	v_mov_b32_e32 v127, v2
	v_mov_b32_e32 v128, v2
	v_mov_b32_e32 v129, v2

.LBB0_474:
	v_lshl_add_u32 v162, s26, 8, v165
	s_and_b32 s99, s48, 1
	s_lshl_b32 s99, s99, 12
	s_add_i32 s99, s99, 0x21000
	v_lshl_add_u32 v252, v165, 4, s99
	v_ashrrev_i32_e32 v163, 31, v162
	v_lshl_add_u64 v[148:149], v[162:163], 4, s[76:77]
	ds_read_b128 v[172:175], v252
	v_or_b32_e32 v160, 16, v162
	v_ashrrev_i32_e32 v161, 31, v160
	v_lshl_add_u64 v[148:149], v[160:161], 4, s[76:77]
	v_or_b32_e32 v158, 32, v162
	ds_read_b128 v[176:179], v252 offset:256
	v_ashrrev_i32_e32 v159, 31, v158
	v_lshl_add_u64 v[148:149], v[158:159], 4, s[76:77]
	v_or_b32_e32 v156, 48, v162
	ds_read_b128 v[180:183], v252 offset:512
	v_ashrrev_i32_e32 v157, 31, v156
	v_lshl_add_u64 v[148:149], v[156:157], 4, s[76:77]
	v_add_u32_e32 v154, 0x80, v162
	ds_read_b128 v[184:187], v252 offset:768
	v_ashrrev_i32_e32 v155, 31, v154
	v_lshl_add_u64 v[148:149], v[154:155], 4, s[76:77]
	v_add_u32_e32 v152, 0x90, v162
	ds_read_b128 v[188:191], v252 offset:2048
	v_ashrrev_i32_e32 v153, 31, v152
	v_add_u32_e32 v150, 0xa0, v162
	v_lshl_add_u64 v[148:149], v[152:153], 4, s[76:77]
	v_ashrrev_i32_e32 v151, 31, v150
	ds_read_b128 v[192:195], v252 offset:2304
	v_lshl_add_u64 v[148:149], v[150:151], 4, s[76:77]
	ds_read_b128 v[196:199], v252 offset:2560
	v_add_u32_e32 v148, 0xb0, v162
	v_ashrrev_i32_e32 v149, 31, v148
	v_lshl_add_u64 v[200:201], v[148:149], 4, s[76:77]
	ds_read_b128 v[200:203], v252 offset:2816
	v_pk_mul_f32 v[114:115], v[118:119], v[114:115]
	v_pk_mul_f32 v[116:117], v[120:121], v[116:117]
	v_pk_mul_f32 v[124:125], v[128:129], v[124:125]
	v_pk_mul_f32 v[122:123], v[126:127], v[122:123]
	s_lshl_b32 s2, s27, 7
	s_ashr_i32 s3, s2, 31
	s_lshl_b64 s[26:27], s[2:3], 1
	v_pk_mul_f32 v[100:101], v[104:105], v[100:101]
	v_pk_mul_f32 v[98:99], v[102:103], v[98:99]
	v_pk_mul_f32 v[108:109], v[112:113], v[108:109]
	v_pk_mul_f32 v[106:107], v[110:111], v[106:107]
	v_pk_mul_f32 v[84:85], v[88:89], v[84:85]
	v_pk_mul_f32 v[82:83], v[86:87], v[82:83]
	v_pk_mul_f32 v[92:93], v[96:97], v[92:93]
	v_pk_mul_f32 v[90:91], v[94:95], v[90:91]
	v_pk_mul_f32 v[68:69], v[72:73], v[68:69]
	v_pk_mul_f32 v[66:67], v[70:71], v[66:67]
	v_pk_mul_f32 v[76:77], v[80:81], v[76:77]
	v_pk_mul_f32 v[74:75], v[78:79], v[74:75]
	v_pk_mul_f32 v[52:53], v[56:57], v[52:53]
	v_pk_mul_f32 v[50:51], v[54:55], v[50:51]
	v_pk_mul_f32 v[60:61], v[64:65], v[60:61]
	v_pk_mul_f32 v[58:59], v[62:63], v[58:59]
	v_pk_mul_f32 v[36:37], v[40:41], v[36:37]
	v_pk_mul_f32 v[34:35], v[38:39], v[34:35]
	v_pk_mul_f32 v[44:45], v[48:49], v[44:45]
	v_pk_mul_f32 v[42:43], v[46:47], v[42:43]
	v_pk_mul_f32 v[20:21], v[24:25], v[20:21]
	v_pk_mul_f32 v[18:19], v[22:23], v[18:19]
	v_pk_mul_f32 v[28:29], v[32:33], v[28:29]
	v_pk_mul_f32 v[26:27], v[30:31], v[26:27]
	v_pk_mul_f32 v[4:5], v[8:9], v[4:5]
	v_pk_mul_f32 v[2:3], v[6:7], v[2:3]
	v_pk_mul_f32 v[12:13], v[16:17], v[12:13]
	v_pk_mul_f32 v[10:11], v[14:15], v[10:11]
	s_mov_b64 s[2:3], -1
	s_andn2_b64 vcc, exec, s[4:5]
	s_waitcnt lgkmcnt(0)
	v_mov_b32_e32 v204, v173
	v_mov_b32_e32 v205, v174
	v_mov_b32_e32 v173, v175
	v_pk_add_f32 v[172:173], v[204:205], v[172:173]
	s_nop 0
	v_add_f32_e32 v149, v172, v173
	v_fmamk_f32 v149, v149, 0x3a800000, v170
	v_mov_b32_e32 v172, v177
	v_mov_b32_e32 v173, v178
	v_mov_b32_e32 v177, v179
	v_rsq_f32_e32 v163, v149
	v_pk_add_f32 v[172:173], v[172:173], v[176:177]
	v_mul_f32_e32 v174, 0xbfb8aa3b, v163
	v_add_f32_e32 v149, v172, v173
	v_mov_b32_e32 v172, v181
	v_mov_b32_e32 v173, v182
	v_mov_b32_e32 v181, v183
	v_fmamk_f32 v149, v149, 0x3a800000, v170
	v_pk_add_f32 v[172:173], v[172:173], v[180:181]
	v_rsq_f32_e32 v161, v149
	v_add_f32_e32 v149, v172, v173
	v_mov_b32_e32 v172, v185
	v_mov_b32_e32 v173, v186
	v_mov_b32_e32 v185, v187
	v_fmamk_f32 v149, v149, 0x3a800000, v170
	v_pk_add_f32 v[172:173], v[172:173], v[184:185]
	v_rsq_f32_e32 v159, v149
	v_add_f32_e32 v149, v172, v173
	v_mov_b32_e32 v172, v189
	v_mov_b32_e32 v173, v190
	v_mov_b32_e32 v189, v191
	v_pk_mul_f32 v[118:119], v[118:119], v[174:175] op_sel_hi:[1,0]
	v_fmamk_f32 v149, v149, 0x3a800000, v170
	v_pk_add_f32 v[172:173], v[172:173], v[188:189]
	v_pk_mul_f32 v[120:121], v[120:121], v[174:175] op_sel_hi:[1,0]
	v_exp_f32_e32 v118, v118
	v_exp_f32_e32 v119, v119
	v_rsq_f32_e32 v157, v149
	v_add_f32_e32 v149, v172, v173
	v_mov_b32_e32 v172, v193
	v_mov_b32_e32 v173, v194
	v_mov_b32_e32 v193, v195
	v_exp_f32_e32 v120, v120
	v_exp_f32_e32 v121, v121
	v_fmamk_f32 v149, v149, 0x3a800000, v170
	v_pk_add_f32 v[172:173], v[172:173], v[192:193]
	v_rsq_f32_e32 v155, v149
	v_add_f32_e32 v149, v172, v173
	v_mov_b32_e32 v172, v197
	v_mov_b32_e32 v173, v198
	v_mov_b32_e32 v197, v199
	v_pk_mul_f32 v[128:129], v[128:129], v[174:175] op_sel_hi:[1,0]
	v_pk_mul_f32 v[126:127], v[126:127], v[174:175] op_sel_hi:[1,0]
	v_fmamk_f32 v149, v149, 0x3a800000, v170
	v_pk_add_f32 v[172:173], v[172:173], v[196:197]
	v_exp_f32_e32 v126, v126
	v_exp_f32_e32 v127, v127
	v_exp_f32_e32 v128, v128
	v_exp_f32_e32 v129, v129
	v_pk_add_f32 v[118:119], v[118:119], 1.0 op_sel_hi:[1,0]
	v_rsq_f32_e32 v153, v149
	v_add_f32_e32 v149, v172, v173
	v_mov_b32_e32 v172, v201
	v_mov_b32_e32 v173, v202
	v_mov_b32_e32 v201, v203
	v_pk_add_f32 v[120:121], v[120:121], 1.0 op_sel_hi:[1,0]
	v_rcp_f32_e32 v118, v118
	v_rcp_f32_e32 v119, v119
	v_fmamk_f32 v149, v149, 0x3a800000, v170
	v_pk_add_f32 v[172:173], v[172:173], v[200:201]
	v_rcp_f32_e32 v120, v120
	v_rcp_f32_e32 v121, v121
	v_rsq_f32_e32 v151, v149
	v_add_f32_e32 v149, v172, v173
	v_mul_f32_e32 v172, v163, v163
	v_pk_add_f32 v[128:129], v[128:129], 1.0 op_sel_hi:[1,0]
	v_pk_add_f32 v[126:127], v[126:127], 1.0 op_sel_hi:[1,0]
	v_pk_mul_f32 v[114:115], v[114:115], v[172:173] op_sel_hi:[1,0]
	v_rcp_f32_e32 v126, v126
	v_rcp_f32_e32 v127, v127
	v_rcp_f32_e32 v128, v128
	v_rcp_f32_e32 v129, v129
	v_pk_mul_f32 v[116:117], v[116:117], v[172:173] op_sel_hi:[1,0]
	v_pk_mul_f32 v[118:119], v[114:115], v[118:119]
	v_mov_b64_e32 v[114:115], s[12:13]
	v_pk_mul_f32 v[120:121], v[116:117], v[120:121]
	v_mad_i64_i32 v[116:117], s[0:1], v162, s47, v[114:115]
	v_lshl_add_u64 v[116:117], v[116:117], 0, s[26:27]
	v_pk_mul_f32 v[122:123], v[122:123], v[172:173] op_sel_hi:[1,0]
	v_pk_mul_f32 v[124:125], v[124:125], v[172:173] op_sel_hi:[1,0]
	v_lshl_add_u64 v[116:117], v[116:117], 0, s[8:9]
	v_pk_mul_f32 v[124:125], v[124:125], v[128:129]
	v_pk_mul_f32 v[122:123], v[122:123], v[126:127]
	v_lshl_add_u64 v[126:127], v[116:117], 0, v[138:139]
	v_cvt_pk_bf16_f32 v116, v122, v123
	v_cvt_pk_bf16_f32 v117, v124, v125
	v_cvt_pk_bf16_f32 v118, v118, v119
	v_cvt_pk_bf16_f32 v119, v120, v121
	global_store_dwordx4 v[126:127], v[116:119], off
	v_fmamk_f32 v149, v149, 0x3a800000, v170
	v_rsq_f32_e32 v149, v149
	v_mul_f32_e32 v118, 0xbfb8aa3b, v161
	v_pk_mul_f32 v[104:105], v[104:105], v[118:119] op_sel_hi:[1,0]
	v_pk_mul_f32 v[102:103], v[102:103], v[118:119] op_sel_hi:[1,0]
	v_exp_f32_e32 v104, v104
	v_exp_f32_e32 v102, v102
	v_exp_f32_e32 v103, v103
	v_exp_f32_e32 v105, v105
	v_pk_mul_f32 v[112:113], v[112:113], v[118:119] op_sel_hi:[1,0]
	v_pk_mul_f32 v[110:111], v[110:111], v[118:119] op_sel_hi:[1,0]
	v_exp_f32_e32 v112, v112
	v_exp_f32_e32 v110, v110
	v_exp_f32_e32 v111, v111
	v_exp_f32_e32 v113, v113
	v_pk_add_f32 v[104:105], v[104:105], 1.0 op_sel_hi:[1,0]
	v_pk_add_f32 v[102:103], v[102:103], 1.0 op_sel_hi:[1,0]
	v_rcp_f32_e32 v104, v104
	v_rcp_f32_e32 v102, v102
	v_rcp_f32_e32 v103, v103
	v_rcp_f32_e32 v105, v105
	v_mul_f32_e32 v116, v161, v161
	v_pk_add_f32 v[112:113], v[112:113], 1.0 op_sel_hi:[1,0]
	v_pk_add_f32 v[110:111], v[110:111], 1.0 op_sel_hi:[1,0]
	v_rcp_f32_e32 v112, v112
	v_rcp_f32_e32 v110, v110
	v_rcp_f32_e32 v111, v111
	v_rcp_f32_e32 v113, v113
	v_pk_mul_f32 v[98:99], v[98:99], v[116:117] op_sel_hi:[1,0]
	v_pk_mul_f32 v[100:101], v[100:101], v[116:117] op_sel_hi:[1,0]
	v_pk_mul_f32 v[106:107], v[106:107], v[116:117] op_sel_hi:[1,0]
	v_pk_mul_f32 v[104:105], v[100:101], v[104:105]
	v_pk_mul_f32 v[100:101], v[98:99], v[102:103]
	v_mad_i64_i32 v[98:99], s[0:1], v160, s47, v[114:115]
	v_lshl_add_u64 v[98:99], v[98:99], 0, s[26:27]
	v_pk_mul_f32 v[108:109], v[108:109], v[116:117] op_sel_hi:[1,0]
	v_lshl_add_u64 v[98:99], v[98:99], 0, s[8:9]
	v_pk_mul_f32 v[108:109], v[108:109], v[112:113]
	v_pk_mul_f32 v[106:107], v[106:107], v[110:111]
	v_lshl_add_u64 v[102:103], v[98:99], 0, v[138:139]
	v_cvt_pk_bf16_f32 v98, v106, v107
	v_cvt_pk_bf16_f32 v99, v108, v109
	v_cvt_pk_bf16_f32 v100, v100, v101
	v_cvt_pk_bf16_f32 v101, v104, v105
	global_store_dwordx4 v[102:103], v[98:101], off
	s_nop 1
	v_mul_f32_e32 v100, 0xbfb8aa3b, v159
	v_pk_mul_f32 v[88:89], v[88:89], v[100:101] op_sel_hi:[1,0]
	v_pk_mul_f32 v[86:87], v[86:87], v[100:101] op_sel_hi:[1,0]
	v_exp_f32_e32 v88, v88
	v_exp_f32_e32 v86, v86
	v_exp_f32_e32 v87, v87
	v_exp_f32_e32 v89, v89
	v_pk_mul_f32 v[96:97], v[96:97], v[100:101] op_sel_hi:[1,0]
	v_pk_mul_f32 v[94:95], v[94:95], v[100:101] op_sel_hi:[1,0]
	v_exp_f32_e32 v96, v96
	v_exp_f32_e32 v94, v94
	v_exp_f32_e32 v95, v95
	v_exp_f32_e32 v97, v97
	v_pk_add_f32 v[88:89], v[88:89], 1.0 op_sel_hi:[1,0]
	v_pk_add_f32 v[86:87], v[86:87], 1.0 op_sel_hi:[1,0]
	v_rcp_f32_e32 v88, v88
	v_rcp_f32_e32 v86, v86
	v_rcp_f32_e32 v87, v87
	v_rcp_f32_e32 v89, v89
	v_mul_f32_e32 v98, v159, v159
	v_pk_add_f32 v[96:97], v[96:97], 1.0 op_sel_hi:[1,0]
	v_pk_add_f32 v[94:95], v[94:95], 1.0 op_sel_hi:[1,0]
	v_rcp_f32_e32 v96, v96
	v_rcp_f32_e32 v94, v94
	v_rcp_f32_e32 v95, v95
	v_rcp_f32_e32 v97, v97
	v_pk_mul_f32 v[82:83], v[82:83], v[98:99] op_sel_hi:[1,0]
	v_pk_mul_f32 v[84:85], v[84:85], v[98:99] op_sel_hi:[1,0]
	v_pk_mul_f32 v[90:91], v[90:91], v[98:99] op_sel_hi:[1,0]
	v_pk_mul_f32 v[88:89], v[84:85], v[88:89]
	v_pk_mul_f32 v[84:85], v[82:83], v[86:87]
	v_mad_i64_i32 v[82:83], s[0:1], v158, s47, v[114:115]
	v_lshl_add_u64 v[82:83], v[82:83], 0, s[26:27]
	v_pk_mul_f32 v[92:93], v[92:93], v[98:99] op_sel_hi:[1,0]
	v_lshl_add_u64 v[82:83], v[82:83], 0, s[8:9]
	v_pk_mul_f32 v[92:93], v[92:93], v[96:97]
	v_pk_mul_f32 v[90:91], v[90:91], v[94:95]
	v_lshl_add_u64 v[86:87], v[82:83], 0, v[138:139]
	v_cvt_pk_bf16_f32 v82, v90, v91
	v_cvt_pk_bf16_f32 v83, v92, v93
	v_cvt_pk_bf16_f32 v84, v84, v85
	v_cvt_pk_bf16_f32 v85, v88, v89
	global_store_dwordx4 v[86:87], v[82:85], off
	s_nop 1
	v_mul_f32_e32 v84, 0xbfb8aa3b, v157
	v_pk_mul_f32 v[72:73], v[72:73], v[84:85] op_sel_hi:[1,0]
	v_pk_mul_f32 v[70:71], v[70:71], v[84:85] op_sel_hi:[1,0]
	v_exp_f32_e32 v72, v72
	v_exp_f32_e32 v70, v70
	v_exp_f32_e32 v71, v71
	v_exp_f32_e32 v73, v73
	v_pk_mul_f32 v[80:81], v[80:81], v[84:85] op_sel_hi:[1,0]
	v_pk_mul_f32 v[78:79], v[78:79], v[84:85] op_sel_hi:[1,0]
	v_exp_f32_e32 v80, v80
	v_exp_f32_e32 v78, v78
	v_exp_f32_e32 v79, v79
	v_exp_f32_e32 v81, v81
	v_pk_add_f32 v[72:73], v[72:73], 1.0 op_sel_hi:[1,0]
	v_pk_add_f32 v[70:71], v[70:71], 1.0 op_sel_hi:[1,0]
	v_rcp_f32_e32 v72, v72
	v_rcp_f32_e32 v70, v70
	v_rcp_f32_e32 v71, v71
	v_rcp_f32_e32 v73, v73
	v_mul_f32_e32 v82, v157, v157
	v_pk_add_f32 v[80:81], v[80:81], 1.0 op_sel_hi:[1,0]
	v_pk_add_f32 v[78:79], v[78:79], 1.0 op_sel_hi:[1,0]
	v_rcp_f32_e32 v80, v80
	v_rcp_f32_e32 v78, v78
	v_rcp_f32_e32 v79, v79
	v_rcp_f32_e32 v81, v81
	v_pk_mul_f32 v[66:67], v[66:67], v[82:83] op_sel_hi:[1,0]
	v_pk_mul_f32 v[68:69], v[68:69], v[82:83] op_sel_hi:[1,0]
	v_pk_mul_f32 v[74:75], v[74:75], v[82:83] op_sel_hi:[1,0]
	v_pk_mul_f32 v[72:73], v[68:69], v[72:73]
	v_pk_mul_f32 v[68:69], v[66:67], v[70:71]
	v_mad_i64_i32 v[66:67], s[0:1], v156, s47, v[114:115]
	v_lshl_add_u64 v[66:67], v[66:67], 0, s[26:27]
	v_pk_mul_f32 v[76:77], v[76:77], v[82:83] op_sel_hi:[1,0]
	v_lshl_add_u64 v[66:67], v[66:67], 0, s[8:9]
	v_pk_mul_f32 v[76:77], v[76:77], v[80:81]
	v_pk_mul_f32 v[74:75], v[74:75], v[78:79]
	v_lshl_add_u64 v[70:71], v[66:67], 0, v[138:139]
	v_cvt_pk_bf16_f32 v66, v74, v75
	v_cvt_pk_bf16_f32 v67, v76, v77
	v_cvt_pk_bf16_f32 v68, v68, v69
	v_cvt_pk_bf16_f32 v69, v72, v73
	global_store_dwordx4 v[70:71], v[66:69], off
	s_nop 1
	v_mul_f32_e32 v68, 0xbfb8aa3b, v155
	v_pk_mul_f32 v[56:57], v[56:57], v[68:69] op_sel_hi:[1,0]
	v_pk_mul_f32 v[54:55], v[54:55], v[68:69] op_sel_hi:[1,0]
	v_exp_f32_e32 v56, v56
	v_exp_f32_e32 v54, v54
	v_exp_f32_e32 v55, v55
	v_exp_f32_e32 v57, v57
	v_pk_mul_f32 v[64:65], v[64:65], v[68:69] op_sel_hi:[1,0]
	v_pk_mul_f32 v[62:63], v[62:63], v[68:69] op_sel_hi:[1,0]
	v_exp_f32_e32 v64, v64
	v_exp_f32_e32 v62, v62
	v_exp_f32_e32 v63, v63
	v_exp_f32_e32 v65, v65
	v_pk_add_f32 v[56:57], v[56:57], 1.0 op_sel_hi:[1,0]
	v_pk_add_f32 v[54:55], v[54:55], 1.0 op_sel_hi:[1,0]
	v_rcp_f32_e32 v56, v56
	v_rcp_f32_e32 v54, v54
	v_rcp_f32_e32 v55, v55
	v_rcp_f32_e32 v57, v57
	v_mul_f32_e32 v66, v155, v155
	v_pk_add_f32 v[64:65], v[64:65], 1.0 op_sel_hi:[1,0]
	v_pk_add_f32 v[62:63], v[62:63], 1.0 op_sel_hi:[1,0]
	v_rcp_f32_e32 v64, v64
	v_rcp_f32_e32 v62, v62
	v_rcp_f32_e32 v63, v63
	v_rcp_f32_e32 v65, v65
	v_pk_mul_f32 v[50:51], v[50:51], v[66:67] op_sel_hi:[1,0]
	v_pk_mul_f32 v[52:53], v[52:53], v[66:67] op_sel_hi:[1,0]
	v_pk_mul_f32 v[58:59], v[58:59], v[66:67] op_sel_hi:[1,0]
	v_pk_mul_f32 v[56:57], v[52:53], v[56:57]
	v_pk_mul_f32 v[52:53], v[50:51], v[54:55]
	v_mad_i64_i32 v[50:51], s[0:1], v154, s47, v[114:115]
	v_lshl_add_u64 v[50:51], v[50:51], 0, s[26:27]
	v_pk_mul_f32 v[60:61], v[60:61], v[66:67] op_sel_hi:[1,0]
	v_lshl_add_u64 v[50:51], v[50:51], 0, s[8:9]
	v_pk_mul_f32 v[60:61], v[60:61], v[64:65]
	v_pk_mul_f32 v[58:59], v[58:59], v[62:63]
	v_lshl_add_u64 v[54:55], v[50:51], 0, v[138:139]
	v_cvt_pk_bf16_f32 v50, v58, v59
	v_cvt_pk_bf16_f32 v51, v60, v61
	v_cvt_pk_bf16_f32 v52, v52, v53
	v_cvt_pk_bf16_f32 v53, v56, v57
	global_store_dwordx4 v[54:55], v[50:53], off
	s_nop 1
	v_mul_f32_e32 v52, 0xbfb8aa3b, v153
	v_pk_mul_f32 v[40:41], v[40:41], v[52:53] op_sel_hi:[1,0]
	v_pk_mul_f32 v[38:39], v[38:39], v[52:53] op_sel_hi:[1,0]
	v_exp_f32_e32 v40, v40
	v_exp_f32_e32 v38, v38
	v_exp_f32_e32 v39, v39
	v_exp_f32_e32 v41, v41
	v_pk_mul_f32 v[48:49], v[48:49], v[52:53] op_sel_hi:[1,0]
	v_pk_mul_f32 v[46:47], v[46:47], v[52:53] op_sel_hi:[1,0]
	v_exp_f32_e32 v48, v48
	v_exp_f32_e32 v46, v46
	v_exp_f32_e32 v47, v47
	v_exp_f32_e32 v49, v49
	v_pk_add_f32 v[40:41], v[40:41], 1.0 op_sel_hi:[1,0]
	v_pk_add_f32 v[38:39], v[38:39], 1.0 op_sel_hi:[1,0]
	v_rcp_f32_e32 v40, v40
	v_rcp_f32_e32 v38, v38
	v_rcp_f32_e32 v39, v39
	v_rcp_f32_e32 v41, v41
	v_mul_f32_e32 v50, v153, v153
	v_pk_add_f32 v[48:49], v[48:49], 1.0 op_sel_hi:[1,0]
	v_pk_add_f32 v[46:47], v[46:47], 1.0 op_sel_hi:[1,0]
	v_rcp_f32_e32 v48, v48
	v_rcp_f32_e32 v46, v46
	v_rcp_f32_e32 v47, v47
	v_rcp_f32_e32 v49, v49
	v_pk_mul_f32 v[34:35], v[34:35], v[50:51] op_sel_hi:[1,0]
	v_pk_mul_f32 v[36:37], v[36:37], v[50:51] op_sel_hi:[1,0]
	v_pk_mul_f32 v[42:43], v[42:43], v[50:51] op_sel_hi:[1,0]
	v_pk_mul_f32 v[40:41], v[36:37], v[40:41]
	v_pk_mul_f32 v[36:37], v[34:35], v[38:39]
	v_mad_i64_i32 v[34:35], s[0:1], v152, s47, v[114:115]
	v_lshl_add_u64 v[34:35], v[34:35], 0, s[26:27]
	v_pk_mul_f32 v[44:45], v[44:45], v[50:51] op_sel_hi:[1,0]
	v_lshl_add_u64 v[34:35], v[34:35], 0, s[8:9]
	v_pk_mul_f32 v[44:45], v[44:45], v[48:49]
	v_pk_mul_f32 v[42:43], v[42:43], v[46:47]
	v_lshl_add_u64 v[38:39], v[34:35], 0, v[138:139]
	v_cvt_pk_bf16_f32 v34, v42, v43
	v_cvt_pk_bf16_f32 v35, v44, v45
	v_cvt_pk_bf16_f32 v36, v36, v37
	v_cvt_pk_bf16_f32 v37, v40, v41
	global_store_dwordx4 v[38:39], v[34:37], off
	s_nop 1
	v_mul_f32_e32 v36, 0xbfb8aa3b, v151
	v_pk_mul_f32 v[24:25], v[24:25], v[36:37] op_sel_hi:[1,0]
	v_pk_mul_f32 v[22:23], v[22:23], v[36:37] op_sel_hi:[1,0]
	v_exp_f32_e32 v24, v24
	v_exp_f32_e32 v22, v22
	v_exp_f32_e32 v23, v23
	v_exp_f32_e32 v25, v25
	v_pk_mul_f32 v[32:33], v[32:33], v[36:37] op_sel_hi:[1,0]
	v_pk_mul_f32 v[30:31], v[30:31], v[36:37] op_sel_hi:[1,0]
	v_exp_f32_e32 v32, v32
	v_exp_f32_e32 v30, v30
	v_exp_f32_e32 v31, v31
	v_exp_f32_e32 v33, v33
	v_pk_add_f32 v[24:25], v[24:25], 1.0 op_sel_hi:[1,0]
	v_pk_add_f32 v[22:23], v[22:23], 1.0 op_sel_hi:[1,0]
	v_rcp_f32_e32 v24, v24
	v_rcp_f32_e32 v22, v22
	v_rcp_f32_e32 v23, v23
	v_rcp_f32_e32 v25, v25
	v_mul_f32_e32 v34, v151, v151
	v_pk_add_f32 v[32:33], v[32:33], 1.0 op_sel_hi:[1,0]
	v_pk_add_f32 v[30:31], v[30:31], 1.0 op_sel_hi:[1,0]
	v_rcp_f32_e32 v32, v32
	v_rcp_f32_e32 v30, v30
	v_rcp_f32_e32 v31, v31
	v_rcp_f32_e32 v33, v33
	v_pk_mul_f32 v[18:19], v[18:19], v[34:35] op_sel_hi:[1,0]
	v_pk_mul_f32 v[20:21], v[20:21], v[34:35] op_sel_hi:[1,0]
	v_pk_mul_f32 v[26:27], v[26:27], v[34:35] op_sel_hi:[1,0]
	v_pk_mul_f32 v[24:25], v[20:21], v[24:25]
	v_pk_mul_f32 v[20:21], v[18:19], v[22:23]
	v_mad_i64_i32 v[18:19], s[0:1], v150, s47, v[114:115]
	v_lshl_add_u64 v[18:19], v[18:19], 0, s[26:27]
	v_pk_mul_f32 v[28:29], v[28:29], v[34:35] op_sel_hi:[1,0]
	v_lshl_add_u64 v[18:19], v[18:19], 0, s[8:9]
	v_pk_mul_f32 v[28:29], v[28:29], v[32:33]
	v_pk_mul_f32 v[26:27], v[26:27], v[30:31]
	v_lshl_add_u64 v[22:23], v[18:19], 0, v[138:139]
	v_cvt_pk_bf16_f32 v18, v26, v27
	v_cvt_pk_bf16_f32 v19, v28, v29
	v_cvt_pk_bf16_f32 v20, v20, v21
	v_cvt_pk_bf16_f32 v21, v24, v25
	global_store_dwordx4 v[22:23], v[18:21], off
	s_nop 1
	v_mul_f32_e32 v20, 0xbfb8aa3b, v149
	v_pk_mul_f32 v[8:9], v[8:9], v[20:21] op_sel_hi:[1,0]
	v_pk_mul_f32 v[6:7], v[6:7], v[20:21] op_sel_hi:[1,0]
	v_exp_f32_e32 v8, v8
	v_exp_f32_e32 v6, v6
	v_exp_f32_e32 v7, v7
	v_exp_f32_e32 v9, v9
	v_pk_mul_f32 v[16:17], v[16:17], v[20:21] op_sel_hi:[1,0]
	v_pk_mul_f32 v[14:15], v[14:15], v[20:21] op_sel_hi:[1,0]
	v_exp_f32_e32 v16, v16
	v_exp_f32_e32 v14, v14
	v_exp_f32_e32 v15, v15
	v_exp_f32_e32 v17, v17
	v_pk_add_f32 v[8:9], v[8:9], 1.0 op_sel_hi:[1,0]
	v_pk_add_f32 v[6:7], v[6:7], 1.0 op_sel_hi:[1,0]
	v_rcp_f32_e32 v8, v8
	v_rcp_f32_e32 v6, v6
	v_rcp_f32_e32 v7, v7
	v_rcp_f32_e32 v9, v9
	v_mul_f32_e32 v18, v149, v149
	v_pk_add_f32 v[16:17], v[16:17], 1.0 op_sel_hi:[1,0]
	v_pk_add_f32 v[14:15], v[14:15], 1.0 op_sel_hi:[1,0]
	v_pk_mul_f32 v[2:3], v[2:3], v[18:19] op_sel_hi:[1,0]
	v_pk_mul_f32 v[4:5], v[4:5], v[18:19] op_sel_hi:[1,0]
	v_rcp_f32_e32 v14, v14
	v_rcp_f32_e32 v15, v15
	v_rcp_f32_e32 v16, v16
	v_rcp_f32_e32 v17, v17
	v_pk_mul_f32 v[8:9], v[4:5], v[8:9]
	v_pk_mul_f32 v[4:5], v[2:3], v[6:7]
	v_mad_i64_i32 v[2:3], s[0:1], v148, s47, v[114:115]
	v_lshl_add_u64 v[2:3], v[2:3], 0, s[26:27]
	v_lshl_add_u64 v[2:3], v[2:3], 0, s[8:9]
	v_pk_mul_f32 v[10:11], v[10:11], v[18:19] op_sel_hi:[1,0]
	v_pk_mul_f32 v[12:13], v[12:13], v[18:19] op_sel_hi:[1,0]
	v_lshl_add_u64 v[6:7], v[2:3], 0, v[138:139]
	v_pk_mul_f32 v[12:13], v[12:13], v[16:17]
	v_pk_mul_f32 v[10:11], v[10:11], v[14:15]
	s_nop 0
	v_cvt_pk_bf16_f32 v2, v10, v11
	v_cvt_pk_bf16_f32 v3, v12, v13
	v_cvt_pk_bf16_f32 v4, v4, v5
	v_cvt_pk_bf16_f32 v5, v8, v9
	global_store_dwordx4 v[6:7], v[2:5], off
	s_cbranch_vccnz .LBB0_467
	s_andn2_b64 vcc, exec, s[10:11]
	s_cbranch_vccnz .LBB0_466
	s_barrier
	s_branch .LBB0_466

.LBB0_1008:
	s_and_b32 s99, s47, 1
	s_lshl_b32 s99, s99, 12
	v_readfirstlane_b32 s100, v0
	s_and_b32 s100, s100, 0xc0
	s_lshl_b32 s100, s100, 4
	s_add_i32 s99, s99, s100
	s_add_i32 m0, s99, 0x21000
	s_lshl_b32 s99, s26, 12
	s_add_u32 s100, s76, s99
	s_addc_u32 s101, s77, 0
	v_and_b32_e32 v129, 0xff, v0
	v_lshlrev_b32_e32 v129, 4, v129
	global_load_lds_dwordx4 v129, s[100:101]
	s_ashr_i32 s21, s20, 31
	s_lshl_b64 s[0:1], s[20:21], 19
	s_add_u32 s22, s78, s0
	s_addc_u32 s23, s79, s1
	s_and_b64 s[0:1], s[4:5], exec
	s_cselect_b32 s21, s23, s29
	s_cselect_b32 s49, s22, s28
	s_ashr_i32 s19, s18, 31
	s_lshl_b64 s[0:1], s[18:19], 19
	s_add_u32 s24, s33, s0
	s_addc_u32 s25, s34, s1
	s_and_b64 s[0:1], s[4:5], exec
	s_cselect_b32 s19, s25, s3
	s_cselect_b32 s50, s24, s2
	s_add_u32 s28, s28, 0x40080
	s_addc_u32 s29, s29, 0
	s_add_u32 s51, s2, 0x100
	v_mov_b32_e32 v2, 0
	s_addc_u32 s52, s3, 0
	s_mov_b32 s53, -2
	v_mov_b32_e32 v3, v2
	v_mov_b32_e32 v4, v2
	v_mov_b32_e32 v5, v2
	v_mov_b32_e32 v10, v2
	v_mov_b32_e32 v11, v2
	v_mov_b32_e32 v12, v2
	v_mov_b32_e32 v13, v2
	v_mov_b32_e32 v18, v2
	v_mov_b32_e32 v19, v2
	v_mov_b32_e32 v20, v2
	v_mov_b32_e32 v21, v2
	v_mov_b32_e32 v26, v2
	v_mov_b32_e32 v27, v2
	v_mov_b32_e32 v28, v2
	v_mov_b32_e32 v29, v2
	v_mov_b32_e32 v34, v2
	v_mov_b32_e32 v35, v2
	v_mov_b32_e32 v36, v2
	v_mov_b32_e32 v37, v2
	v_mov_b32_e32 v42, v2
	v_mov_b32_e32 v43, v2
	v_mov_b32_e32 v44, v2
	v_mov_b32_e32 v45, v2
	v_mov_b32_e32 v50, v2
	v_mov_b32_e32 v51, v2
	v_mov_b32_e32 v52, v2
	v_mov_b32_e32 v53, v2
	v_mov_b32_e32 v58, v2
	v_mov_b32_e32 v59, v2
	v_mov_b32_e32 v60, v2
	v_mov_b32_e32 v61, v2
	v_mov_b32_e32 v6, v2
	v_mov_b32_e32 v7, v2
	v_mov_b32_e32 v8, v2
	v_mov_b32_e32 v9, v2
	v_mov_b32_e32 v14, v2
	v_mov_b32_e32 v15, v2
	v_mov_b32_e32 v16, v2
	v_mov_b32_e32 v17, v2
	v_mov_b32_e32 v22, v2
	v_mov_b32_e32 v23, v2
	v_mov_b32_e32 v24, v2
	v_mov_b32_e32 v25, v2
	v_mov_b32_e32 v30, v2
	v_mov_b32_e32 v31, v2
	v_mov_b32_e32 v32, v2
	v_mov_b32_e32 v33, v2
	v_mov_b32_e32 v38, v2
	v_mov_b32_e32 v39, v2
	v_mov_b32_e32 v40, v2
	v_mov_b32_e32 v41, v2
	v_mov_b32_e32 v46, v2
	v_mov_b32_e32 v47, v2
	v_mov_b32_e32 v48, v2
	v_mov_b32_e32 v49, v2
	v_mov_b32_e32 v54, v2
	v_mov_b32_e32 v55, v2
	v_mov_b32_e32 v56, v2
	v_mov_b32_e32 v57, v2
	v_mov_b32_e32 v62, v2
	v_mov_b32_e32 v63, v2
	v_mov_b32_e32 v64, v2
	v_mov_b32_e32 v65, v2
	v_mov_b32_e32 v66, v2
	v_mov_b32_e32 v67, v2
	v_mov_b32_e32 v68, v2
	v_mov_b32_e32 v69, v2
	v_mov_b32_e32 v74, v2
	v_mov_b32_e32 v75, v2
	v_mov_b32_e32 v76, v2
	v_mov_b32_e32 v77, v2
	v_mov_b32_e32 v82, v2
	v_mov_b32_e32 v83, v2
	v_mov_b32_e32 v84, v2
	v_mov_b32_e32 v85, v2
	v_mov_b32_e32 v90, v2
	v_mov_b32_e32 v91, v2
	v_mov_b32_e32 v92, v2
	v_mov_b32_e32 v93, v2
	v_mov_b32_e32 v98, v2
	v_mov_b32_e32 v99, v2
	v_mov_b32_e32 v100, v2
	v_mov_b32_e32 v101, v2
	v_mov_b32_e32 v106, v2
	v_mov_b32_e32 v107, v2
	v_mov_b32_e32 v108, v2
	v_mov_b32_e32 v109, v2
	v_mov_b32_e32 v114, v2
	v_mov_b32_e32 v115, v2
	v_mov_b32_e32 v116, v2
	v_mov_b32_e32 v117, v2
	v_mov_b32_e32 v122, v2
	v_mov_b32_e32 v123, v2
	v_mov_b32_e32 v124, v2
	v_mov_b32_e32 v125, v2
	v_mov_b32_e32 v70, v2
	v_mov_b32_e32 v71, v2
	v_mov_b32_e32 v72, v2
	v_mov_b32_e32 v73, v2
	v_mov_b32_e32 v78, v2
	v_mov_b32_e32 v79, v2
	v_mov_b32_e32 v80, v2
	v_mov_b32_e32 v81, v2
	v_mov_b32_e32 v86, v2
	v_mov_b32_e32 v87, v2
	v_mov_b32_e32 v88, v2
	v_mov_b32_e32 v89, v2
	v_mov_b32_e32 v94, v2
	v_mov_b32_e32 v95, v2
	v_mov_b32_e32 v96, v2
	v_mov_b32_e32 v97, v2
	v_mov_b32_e32 v102, v2
	v_mov_b32_e32 v103, v2
	v_mov_b32_e32 v104, v2
	v_mov_b32_e32 v105, v2
	v_mov_b32_e32 v110, v2
	v_mov_b32_e32 v111, v2
	v_mov_b32_e32 v112, v2
	v_mov_b32_e32 v113, v2
	v_mov_b32_e32 v118, v2
	v_mov_b32_e32 v119, v2
	v_mov_b32_e32 v120, v2
	v_mov_b32_e32 v121, v2
	v_mov_b32_e32 v126, v2
	v_mov_b32_e32 v127, v2
	v_mov_b32_e32 v128, v2
	v_mov_b32_e32 v129, v2

.LBB0_1012:
	v_lshl_add_u32 v162, s26, 8, v165
	s_and_b32 s99, s47, 1
	s_lshl_b32 s99, s99, 12
	s_add_i32 s99, s99, 0x21000
	v_lshl_add_u32 v252, v165, 4, s99
	v_ashrrev_i32_e32 v163, 31, v162
	v_or_b32_e32 v160, 16, v162
	v_lshl_add_u64 v[148:149], v[162:163], 4, s[76:77]
	v_ashrrev_i32_e32 v161, 31, v160
	v_lshl_add_u64 v[150:151], v[160:161], 4, s[76:77]
	ds_read_b128 v[172:175], v252
	ds_read_b128 v[176:179], v252 offset:256
	v_or_b32_e32 v158, 32, v162
	v_ashrrev_i32_e32 v159, 31, v158
	v_or_b32_e32 v156, 48, v162
	v_add_u32_e32 v154, 0x80, v162
	v_lshl_add_u64 v[148:149], v[158:159], 4, s[76:77]
	v_ashrrev_i32_e32 v157, 31, v156
	v_ashrrev_i32_e32 v155, 31, v154
	v_add_u32_e32 v152, 0x90, v162
	v_lshl_add_u64 v[150:151], v[156:157], 4, s[76:77]
	ds_read_b128 v[180:183], v252 offset:512
	ds_read_b128 v[184:187], v252 offset:768
	v_lshl_add_u64 v[148:149], v[154:155], 4, s[76:77]
	v_ashrrev_i32_e32 v153, 31, v152
	v_lshl_add_u64 v[150:151], v[152:153], 4, s[76:77]
	ds_read_b128 v[188:191], v252 offset:2048
	ds_read_b128 v[192:195], v252 offset:2304
	v_add_u32_e32 v150, 0xa0, v162
	v_ashrrev_i32_e32 v151, 31, v150
	v_lshl_add_u64 v[148:149], v[150:151], 4, s[76:77]
	ds_read_b128 v[196:199], v252 offset:2560
	v_add_u32_e32 v148, 0xb0, v162
	v_ashrrev_i32_e32 v149, 31, v148
	v_lshl_add_u64 v[200:201], v[148:149], 4, s[76:77]
	ds_read_b128 v[200:203], v252 offset:2816
	v_pk_mul_f32 v[124:125], v[128:129], v[124:125]
	v_pk_mul_f32 v[122:123], v[126:127], v[122:123]
	v_pk_mul_f32 v[116:117], v[120:121], v[116:117]
	v_pk_mul_f32 v[114:115], v[118:119], v[114:115]
	s_lshl_b32 s2, s48, 7
	s_ashr_i32 s3, s2, 31
	s_lshl_b64 s[2:3], s[2:3], 1
	v_pk_mul_f32 v[108:109], v[112:113], v[108:109]
	v_pk_mul_f32 v[106:107], v[110:111], v[106:107]
	v_pk_mul_f32 v[100:101], v[104:105], v[100:101]
	v_pk_mul_f32 v[98:99], v[102:103], v[98:99]
	v_pk_mul_f32 v[92:93], v[96:97], v[92:93]
	v_pk_mul_f32 v[90:91], v[94:95], v[90:91]
	v_pk_mul_f32 v[84:85], v[88:89], v[84:85]
	v_pk_mul_f32 v[82:83], v[86:87], v[82:83]
	v_pk_mul_f32 v[76:77], v[80:81], v[76:77]
	v_pk_mul_f32 v[74:75], v[78:79], v[74:75]
	v_pk_mul_f32 v[68:69], v[72:73], v[68:69]
	v_pk_mul_f32 v[66:67], v[70:71], v[66:67]
	v_pk_mul_f32 v[60:61], v[64:65], v[60:61]
	v_pk_mul_f32 v[58:59], v[62:63], v[58:59]
	v_pk_mul_f32 v[52:53], v[56:57], v[52:53]
	v_pk_mul_f32 v[50:51], v[54:55], v[50:51]
	v_pk_mul_f32 v[44:45], v[48:49], v[44:45]
	v_pk_mul_f32 v[42:43], v[46:47], v[42:43]
	v_pk_mul_f32 v[36:37], v[40:41], v[36:37]
	v_pk_mul_f32 v[34:35], v[38:39], v[34:35]
	v_pk_mul_f32 v[28:29], v[32:33], v[28:29]
	v_pk_mul_f32 v[26:27], v[30:31], v[26:27]
	v_pk_mul_f32 v[20:21], v[24:25], v[20:21]
	v_pk_mul_f32 v[18:19], v[22:23], v[18:19]
	v_pk_mul_f32 v[12:13], v[16:17], v[12:13]
	v_pk_mul_f32 v[10:11], v[14:15], v[10:11]
	v_pk_mul_f32 v[4:5], v[8:9], v[4:5]
	v_pk_mul_f32 v[2:3], v[6:7], v[2:3]
	s_andn2_b64 vcc, exec, s[4:5]
	s_waitcnt lgkmcnt(0)
	v_mov_b32_e32 v204, v173
	v_mov_b32_e32 v205, v174
	v_mov_b32_e32 v173, v175
	v_pk_add_f32 v[172:173], v[204:205], v[172:173]
	v_mov_b32_e32 v174, v177
	v_add_f32_e32 v149, v172, v173
	v_fmamk_f32 v149, v149, 0x3a800000, v170
	v_rsq_f32_e32 v171, v149
	v_mov_b32_e32 v175, v178
	v_mov_b32_e32 v177, v179
	v_mov_b32_e32 v178, v181
	v_mov_b32_e32 v179, v182
	v_mov_b32_e32 v181, v183
	v_mov_b32_e32 v182, v185
	v_mov_b32_e32 v183, v186
	v_mov_b32_e32 v185, v187
	v_mov_b32_e32 v186, v189
	v_mov_b32_e32 v187, v190
	v_mov_b32_e32 v189, v191
	v_pk_add_f32 v[172:173], v[174:175], v[176:177]
	v_pk_add_f32 v[174:175], v[178:179], v[180:181]
	v_pk_add_f32 v[176:177], v[182:183], v[184:185]
	v_pk_add_f32 v[178:179], v[186:187], v[188:189]
	v_add_f32_e32 v153, v174, v175
	v_mul_f32_e32 v174, 0xbfb8aa3b, v171
	v_add_f32_e32 v155, v176, v177
	v_add_f32_e32 v157, v178, v179
	v_pk_mul_f32 v[176:177], v[128:129], v[174:175] op_sel_hi:[1,0]
	v_pk_mul_f32 v[178:179], v[126:127], v[174:175] op_sel_hi:[1,0]
	v_exp_f32_e32 v176, v176
	v_exp_f32_e32 v178, v178
	v_exp_f32_e32 v177, v177
	v_exp_f32_e32 v179, v179
	v_add_f32_e32 v151, v172, v173
	v_fmamk_f32 v149, v151, 0x3a800000, v170
	v_fmamk_f32 v151, v153, 0x3a800000, v170
	v_rsq_f32_e32 v173, v151
	v_pk_add_f32 v[126:127], v[176:177], 1.0 op_sel_hi:[1,0]
	v_pk_add_f32 v[128:129], v[178:179], 1.0 op_sel_hi:[1,0]
	v_rcp_f32_e32 v126, v126
	v_rcp_f32_e32 v128, v128
	v_rcp_f32_e32 v127, v127
	v_rcp_f32_e32 v129, v129
	v_mul_f32_e32 v172, v171, v171
	v_pk_mul_f32 v[122:123], v[122:123], v[172:173] op_sel_hi:[1,0]
	v_pk_mul_f32 v[124:125], v[124:125], v[172:173] op_sel_hi:[1,0]
	v_pk_mul_f32 v[122:123], v[122:123], v[128:129]
	v_pk_mul_f32 v[124:125], v[124:125], v[126:127]
	v_pk_mul_f32 v[126:127], v[120:121], v[174:175] op_sel_hi:[1,0]
	v_pk_mul_f32 v[128:129], v[118:119], v[174:175] op_sel_hi:[1,0]
	v_exp_f32_e32 v126, v126
	v_exp_f32_e32 v128, v128
	v_exp_f32_e32 v127, v127
	v_exp_f32_e32 v129, v129
	v_mov_b32_e32 v190, v193
	v_mov_b32_e32 v191, v194
	v_pk_add_f32 v[118:119], v[126:127], 1.0 op_sel_hi:[1,0]
	v_pk_add_f32 v[120:121], v[128:129], 1.0 op_sel_hi:[1,0]
	v_rcp_f32_e32 v118, v118
	v_rcp_f32_e32 v120, v120
	v_rcp_f32_e32 v119, v119
	v_rcp_f32_e32 v121, v121
	v_mov_b32_e32 v193, v195
	v_mov_b32_e32 v194, v197
	v_mov_b32_e32 v195, v198
	v_mov_b32_e32 v197, v199
	v_mov_b32_e32 v198, v201
	v_mov_b32_e32 v199, v202
	v_mov_b32_e32 v201, v203
	v_pk_add_f32 v[180:181], v[190:191], v[192:193]
	v_pk_add_f32 v[182:183], v[194:195], v[196:197]
	v_pk_add_f32 v[184:185], v[198:199], v[200:201]
	v_pk_mul_f32 v[114:115], v[114:115], v[172:173] op_sel_hi:[1,0]
	v_pk_mul_f32 v[116:117], v[116:117], v[172:173] op_sel_hi:[1,0]
	v_add_f32_e32 v159, v180, v181
	v_add_f32_e32 v161, v182, v183
	v_add_f32_e32 v163, v184, v185
	v_pk_mul_f32 v[126:127], v[116:117], v[118:119]
	v_pk_mul_f32 v[118:119], v[114:115], v[120:121]
	v_mov_b64_e32 v[114:115], s[12:13]
	v_fmamk_f32 v153, v155, 0x3a800000, v170
	v_fmamk_f32 v155, v157, 0x3a800000, v170
	v_fmamk_f32 v157, v159, 0x3a800000, v170
	v_fmamk_f32 v159, v161, 0x3a800000, v170
	v_fmamk_f32 v161, v163, 0x3a800000, v170
	v_rsq_f32_e32 v163, v149
	v_mad_i64_i32 v[116:117], s[0:1], v162, s46, v[114:115]
	v_lshl_add_u64 v[116:117], v[116:117], 0, s[2:3]
	v_lshl_add_u64 v[116:117], v[116:117], 0, s[8:9]
	v_lshl_add_u64 v[120:121], v[116:117], 0, v[138:139]
	v_cvt_pk_bf16_f32 v116, v122, v123
	v_cvt_pk_bf16_f32 v117, v124, v125
	v_cvt_pk_bf16_f32 v118, v118, v119
	v_cvt_pk_bf16_f32 v119, v126, v127
	global_store_dwordx4 v[120:121], v[116:119], off
	v_rsq_f32_e32 v153, v153
	v_rsq_f32_e32 v155, v155
	v_mul_f32_e32 v118, 0xbfb8aa3b, v163
	v_pk_mul_f32 v[120:121], v[112:113], v[118:119] op_sel_hi:[1,0]
	v_pk_mul_f32 v[122:123], v[110:111], v[118:119] op_sel_hi:[1,0]
	v_exp_f32_e32 v120, v120
	v_exp_f32_e32 v122, v122
	v_exp_f32_e32 v121, v121
	v_exp_f32_e32 v123, v123
	v_mul_f32_e32 v116, v163, v163
	v_pk_mul_f32 v[106:107], v[106:107], v[116:117] op_sel_hi:[1,0]
	v_pk_add_f32 v[110:111], v[120:121], 1.0 op_sel_hi:[1,0]
	v_pk_add_f32 v[112:113], v[122:123], 1.0 op_sel_hi:[1,0]
	v_rcp_f32_e32 v110, v110
	v_rcp_f32_e32 v112, v112
	v_rcp_f32_e32 v111, v111
	v_rcp_f32_e32 v113, v113
	v_pk_mul_f32 v[108:109], v[108:109], v[116:117] op_sel_hi:[1,0]
	v_pk_mul_f32 v[98:99], v[98:99], v[116:117] op_sel_hi:[1,0]
	v_pk_mul_f32 v[108:109], v[108:109], v[110:111]
	v_pk_mul_f32 v[106:107], v[106:107], v[112:113]
	v_pk_mul_f32 v[110:111], v[104:105], v[118:119] op_sel_hi:[1,0]
	v_pk_mul_f32 v[112:113], v[102:103], v[118:119] op_sel_hi:[1,0]
	v_exp_f32_e32 v110, v110
	v_exp_f32_e32 v112, v112
	v_exp_f32_e32 v111, v111
	v_exp_f32_e32 v113, v113
	v_pk_mul_f32 v[100:101], v[100:101], v[116:117] op_sel_hi:[1,0]
	v_rsq_f32_e32 v157, v157
	v_pk_add_f32 v[102:103], v[110:111], 1.0 op_sel_hi:[1,0]
	v_pk_add_f32 v[104:105], v[112:113], 1.0 op_sel_hi:[1,0]
	v_rcp_f32_e32 v102, v102
	v_rcp_f32_e32 v104, v104
	v_rcp_f32_e32 v103, v103
	v_rcp_f32_e32 v105, v105
	v_rsq_f32_e32 v151, v159
	v_rsq_f32_e32 v149, v161
	v_pk_mul_f32 v[102:103], v[100:101], v[102:103]
	v_pk_mul_f32 v[100:101], v[98:99], v[104:105]
	v_mad_i64_i32 v[98:99], s[0:1], v160, s46, v[114:115]
	v_lshl_add_u64 v[98:99], v[98:99], 0, s[2:3]
	v_lshl_add_u64 v[98:99], v[98:99], 0, s[8:9]
	v_lshl_add_u64 v[104:105], v[98:99], 0, v[138:139]
	v_cvt_pk_bf16_f32 v98, v106, v107
	v_cvt_pk_bf16_f32 v99, v108, v109
	v_cvt_pk_bf16_f32 v100, v100, v101
	v_cvt_pk_bf16_f32 v101, v102, v103
	global_store_dwordx4 v[104:105], v[98:101], off
	s_nop 1
	v_mul_f32_e32 v100, 0xbfb8aa3b, v173
	v_pk_mul_f32 v[102:103], v[96:97], v[100:101] op_sel_hi:[1,0]
	v_pk_mul_f32 v[104:105], v[94:95], v[100:101] op_sel_hi:[1,0]
	v_exp_f32_e32 v102, v102
	v_exp_f32_e32 v104, v104
	v_exp_f32_e32 v103, v103
	v_exp_f32_e32 v105, v105
	v_mul_f32_e32 v98, v173, v173
	v_pk_mul_f32 v[90:91], v[90:91], v[98:99] op_sel_hi:[1,0]
	v_pk_add_f32 v[94:95], v[102:103], 1.0 op_sel_hi:[1,0]
	v_pk_add_f32 v[96:97], v[104:105], 1.0 op_sel_hi:[1,0]
	v_rcp_f32_e32 v94, v94
	v_rcp_f32_e32 v96, v96
	v_rcp_f32_e32 v95, v95
	v_rcp_f32_e32 v97, v97
	v_pk_mul_f32 v[92:93], v[92:93], v[98:99] op_sel_hi:[1,0]
	v_pk_mul_f32 v[82:83], v[82:83], v[98:99] op_sel_hi:[1,0]
	v_pk_mul_f32 v[92:93], v[92:93], v[94:95]
	v_pk_mul_f32 v[90:91], v[90:91], v[96:97]
	v_pk_mul_f32 v[94:95], v[88:89], v[100:101] op_sel_hi:[1,0]
	v_pk_mul_f32 v[96:97], v[86:87], v[100:101] op_sel_hi:[1,0]
	v_exp_f32_e32 v94, v94
	v_exp_f32_e32 v96, v96
	v_exp_f32_e32 v95, v95
	v_exp_f32_e32 v97, v97
	v_pk_mul_f32 v[84:85], v[84:85], v[98:99] op_sel_hi:[1,0]
	v_pk_add_f32 v[86:87], v[94:95], 1.0 op_sel_hi:[1,0]
	v_pk_add_f32 v[88:89], v[96:97], 1.0 op_sel_hi:[1,0]
	v_rcp_f32_e32 v86, v86
	v_rcp_f32_e32 v88, v88
	v_rcp_f32_e32 v87, v87
	v_rcp_f32_e32 v89, v89
	v_pk_mul_f32 v[86:87], v[84:85], v[86:87]
	v_pk_mul_f32 v[84:85], v[82:83], v[88:89]
	v_mad_i64_i32 v[82:83], s[0:1], v158, s46, v[114:115]
	v_lshl_add_u64 v[82:83], v[82:83], 0, s[2:3]
	v_lshl_add_u64 v[82:83], v[82:83], 0, s[8:9]
	v_lshl_add_u64 v[88:89], v[82:83], 0, v[138:139]
	v_cvt_pk_bf16_f32 v82, v90, v91
	v_cvt_pk_bf16_f32 v83, v92, v93
	v_cvt_pk_bf16_f32 v84, v84, v85
	v_cvt_pk_bf16_f32 v85, v86, v87
	global_store_dwordx4 v[88:89], v[82:85], off
	s_nop 1
	v_mul_f32_e32 v84, 0xbfb8aa3b, v153
	v_pk_mul_f32 v[86:87], v[80:81], v[84:85] op_sel_hi:[1,0]
	v_pk_mul_f32 v[88:89], v[78:79], v[84:85] op_sel_hi:[1,0]
	v_exp_f32_e32 v86, v86
	v_exp_f32_e32 v88, v88
	v_exp_f32_e32 v87, v87
	v_exp_f32_e32 v89, v89
	v_mul_f32_e32 v82, v153, v153
	v_pk_mul_f32 v[74:75], v[74:75], v[82:83] op_sel_hi:[1,0]
	v_pk_add_f32 v[78:79], v[86:87], 1.0 op_sel_hi:[1,0]
	v_pk_add_f32 v[80:81], v[88:89], 1.0 op_sel_hi:[1,0]
	v_rcp_f32_e32 v78, v78
	v_rcp_f32_e32 v80, v80
	v_rcp_f32_e32 v79, v79
	v_rcp_f32_e32 v81, v81
	v_pk_mul_f32 v[76:77], v[76:77], v[82:83] op_sel_hi:[1,0]
	v_pk_mul_f32 v[66:67], v[66:67], v[82:83] op_sel_hi:[1,0]
	v_pk_mul_f32 v[76:77], v[76:77], v[78:79]
	v_pk_mul_f32 v[74:75], v[74:75], v[80:81]
	v_pk_mul_f32 v[78:79], v[72:73], v[84:85] op_sel_hi:[1,0]
	v_pk_mul_f32 v[80:81], v[70:71], v[84:85] op_sel_hi:[1,0]
	v_exp_f32_e32 v78, v78
	v_exp_f32_e32 v80, v80
	v_exp_f32_e32 v79, v79
	v_exp_f32_e32 v81, v81
	v_pk_mul_f32 v[68:69], v[68:69], v[82:83] op_sel_hi:[1,0]
	v_pk_add_f32 v[70:71], v[78:79], 1.0 op_sel_hi:[1,0]
	v_pk_add_f32 v[72:73], v[80:81], 1.0 op_sel_hi:[1,0]
	v_rcp_f32_e32 v70, v70
	v_rcp_f32_e32 v72, v72
	v_rcp_f32_e32 v71, v71
	v_rcp_f32_e32 v73, v73
	v_pk_mul_f32 v[70:71], v[68:69], v[70:71]
	v_pk_mul_f32 v[68:69], v[66:67], v[72:73]
	v_mad_i64_i32 v[66:67], s[0:1], v156, s46, v[114:115]
	v_lshl_add_u64 v[66:67], v[66:67], 0, s[2:3]
	v_lshl_add_u64 v[66:67], v[66:67], 0, s[8:9]
	v_lshl_add_u64 v[72:73], v[66:67], 0, v[138:139]
	v_cvt_pk_bf16_f32 v66, v74, v75
	v_cvt_pk_bf16_f32 v67, v76, v77
	v_cvt_pk_bf16_f32 v68, v68, v69
	v_cvt_pk_bf16_f32 v69, v70, v71
	global_store_dwordx4 v[72:73], v[66:69], off
	s_nop 1
	v_mul_f32_e32 v68, 0xbfb8aa3b, v155
	v_pk_mul_f32 v[70:71], v[64:65], v[68:69] op_sel_hi:[1,0]
	v_pk_mul_f32 v[72:73], v[62:63], v[68:69] op_sel_hi:[1,0]
	v_exp_f32_e32 v70, v70
	v_exp_f32_e32 v72, v72
	v_exp_f32_e32 v71, v71
	v_exp_f32_e32 v73, v73
	v_mul_f32_e32 v66, v155, v155
	v_pk_mul_f32 v[58:59], v[58:59], v[66:67] op_sel_hi:[1,0]
	v_pk_add_f32 v[62:63], v[70:71], 1.0 op_sel_hi:[1,0]
	v_pk_add_f32 v[64:65], v[72:73], 1.0 op_sel_hi:[1,0]
	v_rcp_f32_e32 v62, v62
	v_rcp_f32_e32 v64, v64
	v_rcp_f32_e32 v63, v63
	v_rcp_f32_e32 v65, v65
	v_pk_mul_f32 v[60:61], v[60:61], v[66:67] op_sel_hi:[1,0]
	v_pk_mul_f32 v[50:51], v[50:51], v[66:67] op_sel_hi:[1,0]
	v_pk_mul_f32 v[60:61], v[60:61], v[62:63]
	v_pk_mul_f32 v[58:59], v[58:59], v[64:65]
	v_pk_mul_f32 v[62:63], v[56:57], v[68:69] op_sel_hi:[1,0]
	v_pk_mul_f32 v[64:65], v[54:55], v[68:69] op_sel_hi:[1,0]
	v_exp_f32_e32 v62, v62
	v_exp_f32_e32 v64, v64
	v_exp_f32_e32 v63, v63
	v_exp_f32_e32 v65, v65
	v_pk_mul_f32 v[52:53], v[52:53], v[66:67] op_sel_hi:[1,0]
	v_pk_add_f32 v[54:55], v[62:63], 1.0 op_sel_hi:[1,0]
	v_pk_add_f32 v[56:57], v[64:65], 1.0 op_sel_hi:[1,0]
	v_rcp_f32_e32 v54, v54
	v_rcp_f32_e32 v56, v56
	v_rcp_f32_e32 v55, v55
	v_rcp_f32_e32 v57, v57
	v_pk_mul_f32 v[54:55], v[52:53], v[54:55]
	v_pk_mul_f32 v[52:53], v[50:51], v[56:57]
	v_mad_i64_i32 v[50:51], s[0:1], v154, s46, v[114:115]
	v_lshl_add_u64 v[50:51], v[50:51], 0, s[2:3]
	v_lshl_add_u64 v[50:51], v[50:51], 0, s[8:9]
	v_lshl_add_u64 v[56:57], v[50:51], 0, v[138:139]
	v_cvt_pk_bf16_f32 v50, v58, v59
	v_cvt_pk_bf16_f32 v51, v60, v61
	v_cvt_pk_bf16_f32 v52, v52, v53
	v_cvt_pk_bf16_f32 v53, v54, v55
	global_store_dwordx4 v[56:57], v[50:53], off
	s_nop 1
	v_mul_f32_e32 v52, 0xbfb8aa3b, v157
	v_pk_mul_f32 v[54:55], v[48:49], v[52:53] op_sel_hi:[1,0]
	v_pk_mul_f32 v[56:57], v[46:47], v[52:53] op_sel_hi:[1,0]
	v_exp_f32_e32 v54, v54
	v_exp_f32_e32 v56, v56
	v_exp_f32_e32 v55, v55
	v_exp_f32_e32 v57, v57
	v_mul_f32_e32 v50, v157, v157
	v_pk_mul_f32 v[42:43], v[42:43], v[50:51] op_sel_hi:[1,0]
	v_pk_add_f32 v[46:47], v[54:55], 1.0 op_sel_hi:[1,0]
	v_pk_add_f32 v[48:49], v[56:57], 1.0 op_sel_hi:[1,0]
	v_rcp_f32_e32 v46, v46
	v_rcp_f32_e32 v48, v48
	v_rcp_f32_e32 v47, v47
	v_rcp_f32_e32 v49, v49
	v_pk_mul_f32 v[44:45], v[44:45], v[50:51] op_sel_hi:[1,0]
	v_pk_mul_f32 v[34:35], v[34:35], v[50:51] op_sel_hi:[1,0]
	v_pk_mul_f32 v[44:45], v[44:45], v[46:47]
	v_pk_mul_f32 v[42:43], v[42:43], v[48:49]
	v_pk_mul_f32 v[46:47], v[40:41], v[52:53] op_sel_hi:[1,0]
	v_pk_mul_f32 v[48:49], v[38:39], v[52:53] op_sel_hi:[1,0]
	v_exp_f32_e32 v46, v46
	v_exp_f32_e32 v48, v48
	v_exp_f32_e32 v47, v47
	v_exp_f32_e32 v49, v49
	v_pk_mul_f32 v[36:37], v[36:37], v[50:51] op_sel_hi:[1,0]
	v_pk_add_f32 v[38:39], v[46:47], 1.0 op_sel_hi:[1,0]
	v_pk_add_f32 v[40:41], v[48:49], 1.0 op_sel_hi:[1,0]
	v_rcp_f32_e32 v38, v38
	v_rcp_f32_e32 v40, v40
	v_rcp_f32_e32 v39, v39
	v_rcp_f32_e32 v41, v41
	v_pk_mul_f32 v[38:39], v[36:37], v[38:39]
	v_pk_mul_f32 v[36:37], v[34:35], v[40:41]
	v_mad_i64_i32 v[34:35], s[0:1], v152, s46, v[114:115]
	v_lshl_add_u64 v[34:35], v[34:35], 0, s[2:3]
	v_lshl_add_u64 v[34:35], v[34:35], 0, s[8:9]
	v_lshl_add_u64 v[40:41], v[34:35], 0, v[138:139]
	v_cvt_pk_bf16_f32 v34, v42, v43
	v_cvt_pk_bf16_f32 v35, v44, v45
	v_cvt_pk_bf16_f32 v36, v36, v37
	v_cvt_pk_bf16_f32 v37, v38, v39
	global_store_dwordx4 v[40:41], v[34:37], off
	s_nop 1
	v_mul_f32_e32 v36, 0xbfb8aa3b, v151
	v_pk_mul_f32 v[38:39], v[32:33], v[36:37] op_sel_hi:[1,0]
	v_pk_mul_f32 v[40:41], v[30:31], v[36:37] op_sel_hi:[1,0]
	v_exp_f32_e32 v38, v38
	v_exp_f32_e32 v40, v40
	v_exp_f32_e32 v39, v39
	v_exp_f32_e32 v41, v41
	v_mul_f32_e32 v34, v151, v151
	v_pk_mul_f32 v[26:27], v[26:27], v[34:35] op_sel_hi:[1,0]
	v_pk_add_f32 v[30:31], v[38:39], 1.0 op_sel_hi:[1,0]
	v_pk_add_f32 v[32:33], v[40:41], 1.0 op_sel_hi:[1,0]
	v_rcp_f32_e32 v30, v30
	v_rcp_f32_e32 v32, v32
	v_rcp_f32_e32 v31, v31
	v_rcp_f32_e32 v33, v33
	v_pk_mul_f32 v[28:29], v[28:29], v[34:35] op_sel_hi:[1,0]
	v_pk_mul_f32 v[18:19], v[18:19], v[34:35] op_sel_hi:[1,0]
	v_pk_mul_f32 v[28:29], v[28:29], v[30:31]
	v_pk_mul_f32 v[26:27], v[26:27], v[32:33]
	v_pk_mul_f32 v[30:31], v[24:25], v[36:37] op_sel_hi:[1,0]
	v_pk_mul_f32 v[32:33], v[22:23], v[36:37] op_sel_hi:[1,0]
	v_exp_f32_e32 v30, v30
	v_exp_f32_e32 v32, v32
	v_exp_f32_e32 v31, v31
	v_exp_f32_e32 v33, v33
	v_pk_mul_f32 v[20:21], v[20:21], v[34:35] op_sel_hi:[1,0]
	v_pk_add_f32 v[22:23], v[30:31], 1.0 op_sel_hi:[1,0]
	v_pk_add_f32 v[24:25], v[32:33], 1.0 op_sel_hi:[1,0]
	v_rcp_f32_e32 v22, v22
	v_rcp_f32_e32 v24, v24
	v_rcp_f32_e32 v23, v23
	v_rcp_f32_e32 v25, v25
	v_pk_mul_f32 v[22:23], v[20:21], v[22:23]
	v_pk_mul_f32 v[20:21], v[18:19], v[24:25]
	v_mad_i64_i32 v[18:19], s[0:1], v150, s46, v[114:115]
	v_lshl_add_u64 v[18:19], v[18:19], 0, s[2:3]
	v_lshl_add_u64 v[18:19], v[18:19], 0, s[8:9]
	v_lshl_add_u64 v[24:25], v[18:19], 0, v[138:139]
	v_cvt_pk_bf16_f32 v18, v26, v27
	v_cvt_pk_bf16_f32 v19, v28, v29
	v_cvt_pk_bf16_f32 v20, v20, v21
	v_cvt_pk_bf16_f32 v21, v22, v23
	global_store_dwordx4 v[24:25], v[18:21], off
	s_nop 1
	v_mul_f32_e32 v20, 0xbfb8aa3b, v149
	v_pk_mul_f32 v[22:23], v[16:17], v[20:21] op_sel_hi:[1,0]
	v_pk_mul_f32 v[24:25], v[14:15], v[20:21] op_sel_hi:[1,0]
	v_exp_f32_e32 v22, v22
	v_exp_f32_e32 v24, v24
	v_exp_f32_e32 v23, v23
	v_exp_f32_e32 v25, v25
	v_mul_f32_e32 v18, v149, v149
	v_pk_mul_f32 v[10:11], v[10:11], v[18:19] op_sel_hi:[1,0]
	v_pk_add_f32 v[14:15], v[22:23], 1.0 op_sel_hi:[1,0]
	v_pk_add_f32 v[16:17], v[24:25], 1.0 op_sel_hi:[1,0]
	v_rcp_f32_e32 v14, v14
	v_rcp_f32_e32 v16, v16
	v_rcp_f32_e32 v15, v15
	v_rcp_f32_e32 v17, v17
	v_pk_mul_f32 v[12:13], v[12:13], v[18:19] op_sel_hi:[1,0]
	v_pk_mul_f32 v[2:3], v[2:3], v[18:19] op_sel_hi:[1,0]
	v_pk_mul_f32 v[12:13], v[12:13], v[14:15]
	v_pk_mul_f32 v[10:11], v[10:11], v[16:17]
	v_pk_mul_f32 v[14:15], v[8:9], v[20:21] op_sel_hi:[1,0]
	v_pk_mul_f32 v[16:17], v[6:7], v[20:21] op_sel_hi:[1,0]
	v_exp_f32_e32 v14, v14
	v_exp_f32_e32 v16, v16
	v_exp_f32_e32 v15, v15
	v_exp_f32_e32 v17, v17
	v_pk_mul_f32 v[4:5], v[4:5], v[18:19] op_sel_hi:[1,0]
	v_pk_add_f32 v[6:7], v[14:15], 1.0 op_sel_hi:[1,0]
	v_pk_add_f32 v[8:9], v[16:17], 1.0 op_sel_hi:[1,0]
	v_rcp_f32_e32 v6, v6
	v_rcp_f32_e32 v8, v8
	v_rcp_f32_e32 v7, v7
	v_rcp_f32_e32 v9, v9
	v_pk_mul_f32 v[6:7], v[4:5], v[6:7]
	v_pk_mul_f32 v[4:5], v[2:3], v[8:9]
	v_mad_i64_i32 v[2:3], s[0:1], v148, s46, v[114:115]
	v_lshl_add_u64 v[2:3], v[2:3], 0, s[2:3]
	v_lshl_add_u64 v[2:3], v[2:3], 0, s[8:9]
	v_lshl_add_u64 v[8:9], v[2:3], 0, v[138:139]
	s_mov_b64 s[2:3], -1
	v_cvt_pk_bf16_f32 v2, v10, v11
	v_cvt_pk_bf16_f32 v3, v12, v13
	v_cvt_pk_bf16_f32 v4, v4, v5
	v_cvt_pk_bf16_f32 v5, v6, v7
	global_store_dwordx4 v[8:9], v[2:5], off
	s_cbranch_vccnz .LBB0_1005
	s_andn2_b64 vcc, exec, s[10:11]
	s_cbranch_vccnz .LBB0_1004
	s_barrier
	s_branch .LBB0_1004

.LBB0_1213:
	s_and_b32 s99, s56, 1
	s_lshl_b32 s99, s99, 12
	v_readfirstlane_b32 s100, v0
	s_and_b32 s100, s100, 0xc0
	s_lshl_b32 s100, s100, 4
	s_add_i32 s99, s99, s100
	s_add_i32 m0, s99, 0x21000
	s_lshl_b32 s99, s8, 12
	s_add_u32 s100, s76, s99
	s_addc_u32 s101, s77, 0
	v_and_b32_e32 v149, 0xff, v0
	v_lshlrev_b32_e32 v149, 4, v149
	global_load_lds_dwordx4 v149, s[100:101]
	s_ashr_i32 s31, s30, 31
	s_lshl_b64 s[0:1], s[30:31], 19
	s_add_u32 s34, s78, s0
	s_addc_u32 s35, s79, s1
	s_and_b64 s[0:1], s[4:5], exec
	s_cselect_b32 s7, s35, s39
	s_cselect_b32 s9, s34, s38
	s_ashr_i32 s29, s28, 31
	s_lshl_b64 s[0:1], s[28:29], 19
	s_add_u32 s36, s27, s0
	s_addc_u32 s37, s33, s1
	s_and_b64 s[0:1], s[4:5], exec
	s_cselect_b32 s10, s37, s3
	s_cselect_b32 s29, s36, s2
	s_add_u32 s38, s38, 0x40080
	s_addc_u32 s39, s39, 0
	s_add_u32 s31, s2, 0x100
	v_mov_b32_e32 v2, 0
	s_addc_u32 s57, s3, 0
	s_mov_b32 s58, -2
	v_mov_b32_e32 v3, v2
	v_mov_b32_e32 v4, v2
	v_mov_b32_e32 v5, v2
	v_mov_b32_e32 v6, v2
	v_mov_b32_e32 v7, v2
	v_mov_b32_e32 v8, v2
	v_mov_b32_e32 v9, v2
	v_mov_b32_e32 v18, v2
	v_mov_b32_e32 v19, v2
	v_mov_b32_e32 v20, v2
	v_mov_b32_e32 v21, v2
	v_mov_b32_e32 v22, v2
	v_mov_b32_e32 v23, v2
	v_mov_b32_e32 v24, v2
	v_mov_b32_e32 v25, v2
	v_mov_b32_e32 v34, v2
	v_mov_b32_e32 v35, v2
	v_mov_b32_e32 v36, v2
	v_mov_b32_e32 v37, v2
	v_mov_b32_e32 v38, v2
	v_mov_b32_e32 v39, v2
	v_mov_b32_e32 v40, v2
	v_mov_b32_e32 v41, v2
	v_mov_b32_e32 v50, v2
	v_mov_b32_e32 v51, v2
	v_mov_b32_e32 v52, v2
	v_mov_b32_e32 v53, v2
	v_mov_b32_e32 v54, v2
	v_mov_b32_e32 v55, v2
	v_mov_b32_e32 v56, v2
	v_mov_b32_e32 v57, v2
	v_mov_b32_e32 v10, v2
	v_mov_b32_e32 v11, v2
	v_mov_b32_e32 v12, v2
	v_mov_b32_e32 v13, v2
	v_mov_b32_e32 v14, v2
	v_mov_b32_e32 v15, v2
	v_mov_b32_e32 v16, v2
	v_mov_b32_e32 v17, v2
	v_mov_b32_e32 v26, v2
	v_mov_b32_e32 v27, v2
	v_mov_b32_e32 v28, v2
	v_mov_b32_e32 v29, v2
	v_mov_b32_e32 v30, v2
	v_mov_b32_e32 v31, v2
	v_mov_b32_e32 v32, v2
	v_mov_b32_e32 v33, v2
	v_mov_b32_e32 v42, v2
	v_mov_b32_e32 v43, v2
	v_mov_b32_e32 v44, v2
	v_mov_b32_e32 v45, v2
	v_mov_b32_e32 v46, v2
	v_mov_b32_e32 v47, v2
	v_mov_b32_e32 v48, v2
	v_mov_b32_e32 v49, v2
	v_mov_b32_e32 v58, v2
	v_mov_b32_e32 v59, v2
	v_mov_b32_e32 v60, v2
	v_mov_b32_e32 v61, v2
	v_mov_b32_e32 v66, v2
	v_mov_b32_e32 v67, v2
	v_mov_b32_e32 v68, v2
	v_mov_b32_e32 v69, v2
	v_mov_b32_e32 v70, v2
	v_mov_b32_e32 v71, v2
	v_mov_b32_e32 v72, v2
	v_mov_b32_e32 v73, v2
	v_mov_b32_e32 v74, v2
	v_mov_b32_e32 v75, v2
	v_mov_b32_e32 v76, v2
	v_mov_b32_e32 v77, v2
	v_mov_b32_e32 v90, v2
	v_mov_b32_e32 v91, v2
	v_mov_b32_e32 v92, v2
	v_mov_b32_e32 v93, v2
	v_mov_b32_e32 v94, v2
	v_mov_b32_e32 v95, v2
	v_mov_b32_e32 v96, v2
	v_mov_b32_e32 v97, v2
	v_mov_b32_e32 v110, v2
	v_mov_b32_e32 v111, v2
	v_mov_b32_e32 v112, v2
	v_mov_b32_e32 v113, v2
	v_mov_b32_e32 v114, v2
	v_mov_b32_e32 v115, v2
	v_mov_b32_e32 v116, v2
	v_mov_b32_e32 v117, v2
	v_mov_b32_e32 v130, v2
	v_mov_b32_e32 v131, v2
	v_mov_b32_e32 v132, v2
	v_mov_b32_e32 v133, v2
	v_mov_b32_e32 v134, v2
	v_mov_b32_e32 v135, v2
	v_mov_b32_e32 v136, v2
	v_mov_b32_e32 v137, v2
	v_mov_b32_e32 v82, v2
	v_mov_b32_e32 v83, v2
	v_mov_b32_e32 v84, v2
	v_mov_b32_e32 v85, v2
	v_mov_b32_e32 v86, v2
	v_mov_b32_e32 v87, v2
	v_mov_b32_e32 v88, v2
	v_mov_b32_e32 v89, v2
	v_mov_b32_e32 v102, v2
	v_mov_b32_e32 v103, v2
	v_mov_b32_e32 v104, v2
	v_mov_b32_e32 v105, v2
	v_mov_b32_e32 v106, v2
	v_mov_b32_e32 v107, v2
	v_mov_b32_e32 v108, v2
	v_mov_b32_e32 v109, v2
	v_mov_b32_e32 v122, v2
	v_mov_b32_e32 v123, v2
	v_mov_b32_e32 v124, v2
	v_mov_b32_e32 v125, v2
	v_mov_b32_e32 v126, v2
	v_mov_b32_e32 v127, v2
	v_mov_b32_e32 v128, v2
	v_mov_b32_e32 v129, v2
	v_mov_b32_e32 v142, v2
	v_mov_b32_e32 v143, v2
	v_mov_b32_e32 v144, v2
	v_mov_b32_e32 v145, v2
	v_mov_b32_e32 v146, v2
	v_mov_b32_e32 v147, v2
	v_mov_b32_e32 v148, v2
	v_mov_b32_e32 v149, v2

.LBB0_1217:
	s_lshl_b32 s29, s8, 8
	s_add_i32 s29, s29, s47
	v_or_b32_e32 v198, s29, v159
	s_and_b32 s99, s56, 1
	s_lshl_b32 s99, s99, 12
	s_add_i32 s99, s99, 0x21000
	s_lshl_b32 s100, s47, 4
	s_add_i32 s99, s99, s100
	v_lshl_add_u32 v252, v159, 4, s99
	v_ashrrev_i32_e32 v199, 31, v198
	v_or_b32_e32 v192, 16, v198
	v_lshl_add_u64 v[62:63], v[198:199], 4, s[76:77]
	v_ashrrev_i32_e32 v193, 31, v192
	v_lshl_add_u64 v[64:65], v[192:193], 4, s[76:77]
	ds_read_b128 v[194:197], v252
	ds_read_b128 v[154:157], v252 offset:256
	v_or_b32_e32 v190, 32, v198
	v_or_b32_e32 v188, 48, v198
	v_ashrrev_i32_e32 v191, 31, v190
	v_ashrrev_i32_e32 v189, 31, v188
	v_add_u32_e32 v182, 0x80, v198
	v_add_u32_e32 v186, 0x90, v198
	v_lshl_add_u64 v[62:63], v[190:191], 4, s[76:77]
	v_lshl_add_u64 v[64:65], v[188:189], 4, s[76:77]
	v_ashrrev_i32_e32 v183, 31, v182
	v_ashrrev_i32_e32 v187, 31, v186
	v_add_u32_e32 v184, 0xa0, v198
	v_add_u32_e32 v180, 0xb0, v198
	ds_read_b128 v[150:153], v252 offset:512
	ds_read_b128 v[138:141], v252 offset:768
	v_lshl_add_u64 v[62:63], v[182:183], 4, s[76:77]
	v_lshl_add_u64 v[64:65], v[186:187], 4, s[76:77]
	v_ashrrev_i32_e32 v185, 31, v184
	v_ashrrev_i32_e32 v181, 31, v180
	ds_read_b128 v[118:121], v252 offset:2048
	ds_read_b128 v[98:101], v252 offset:2304
	v_lshl_add_u64 v[62:63], v[184:185], 4, s[76:77]
	v_lshl_add_u64 v[64:65], v[180:181], 4, s[76:77]
	ds_read_b128 v[78:81], v252 offset:2560
	s_nop 0
	ds_read_b128 v[62:65], v252 offset:2816
	s_cmp_gt_i32 s6, 7
	s_cselect_b64 s[2:3], -1, 0
	s_lshl_b32 s38, s6, 8
	v_add_u32_e32 v178, s38, v207
	v_lshlrev_b64 v[200:201], 13, v[198:199]
	s_mov_b64 s[8:9], -1
	s_and_b64 vcc, exec, s[2:3]
	v_ashrrev_i32_e32 v179, 31, v178
	s_waitcnt lgkmcnt(0)
	v_mov_b32_e32 v202, v195
	v_mov_b32_e32 v203, v196
	v_mov_b32_e32 v195, v197
	v_pk_add_f32 v[194:195], v[202:203], v[194:195]
	s_nop 0
	v_add_f32_e32 v168, v194, v195
	v_fmamk_f32 v168, v168, 0x3a800000, v211
	v_rsq_f32_e32 v196, v168
	v_lshl_add_u64 v[194:195], s[16:17], 0, v[200:201]
	v_pk_mul_f32 v[200:201], v[148:149], v[196:197] op_sel_hi:[1,0]
	v_pk_mul_f32 v[202:203], v[146:147], v[196:197] op_sel_hi:[1,0]
	v_pk_mul_f32 v[148:149], v[144:145], v[196:197] op_sel_hi:[1,0]
	v_pk_mul_f32 v[146:147], v[142:143], v[196:197] op_sel_hi:[1,0]
	s_cbranch_vccz .LBB0_1219
	v_lshl_add_u64 v[212:213], v[178:179], 1, v[194:195]
	v_cvt_pk_bf16_f32 v142, v202, v203
	v_cvt_pk_bf16_f32 v143, v200, v201
	v_cvt_pk_bf16_f32 v144, v146, v147
	v_cvt_pk_bf16_f32 v145, v148, v149
	global_store_dwordx4 v[212:213], v[142:145], off
	s_mov_b64 s[8:9], 0

.LBB0_1718:
	v_lshl_add_u32 v162, s26, 8, v164
	s_and_b32 s99, s47, 1
	s_lshl_b32 s99, s99, 12
	s_add_i32 s99, s99, 0x21000
	v_lshl_add_u32 v252, v164, 4, s99
	v_ashrrev_i32_e32 v163, 31, v162
	v_or_b32_e32 v160, 16, v162
	v_or_b32_e32 v158, 32, v162
	v_lshl_add_u64 v[148:149], v[162:163], 4, s[76:77]
	v_ashrrev_i32_e32 v161, 31, v160
	v_ashrrev_i32_e32 v159, 31, v158
	v_or_b32_e32 v156, 48, v162
	v_lshl_add_u64 v[150:151], v[160:161], 4, s[76:77]
	ds_read_b128 v[170:173], v252
	ds_read_b128 v[174:177], v252 offset:256
	v_lshl_add_u64 v[148:149], v[158:159], 4, s[76:77]
	v_ashrrev_i32_e32 v157, 31, v156
	v_lshl_add_u64 v[150:151], v[156:157], 4, s[76:77]
	ds_read_b128 v[178:181], v252 offset:512
	ds_read_b128 v[182:185], v252 offset:768
	v_add_u32_e32 v154, 0x80, v162
	v_ashrrev_i32_e32 v155, 31, v154
	v_add_u32_e32 v152, 0x90, v162
	v_lshl_add_u64 v[148:149], v[154:155], 4, s[76:77]
	v_ashrrev_i32_e32 v153, 31, v152
	v_lshl_add_u64 v[150:151], v[152:153], 4, s[76:77]
	ds_read_b128 v[186:189], v252 offset:2048
	ds_read_b128 v[190:193], v252 offset:2304
	v_add_u32_e32 v150, 0xa0, v162
	v_ashrrev_i32_e32 v151, 31, v150
	v_lshl_add_u64 v[148:149], v[150:151], 4, s[76:77]
	ds_read_b128 v[194:197], v252 offset:2560
	v_add_u32_e32 v148, 0xb0, v162
	v_ashrrev_i32_e32 v149, 31, v148
	v_lshl_add_u64 v[198:199], v[148:149], 4, s[76:77]
	ds_read_b128 v[198:201], v252 offset:2816
	v_pk_mul_f32 v[124:125], v[128:129], v[124:125]
	v_pk_mul_f32 v[122:123], v[126:127], v[122:123]
	v_pk_mul_f32 v[116:117], v[120:121], v[116:117]
	v_pk_mul_f32 v[114:115], v[118:119], v[114:115]
	s_lshl_b32 s2, s48, 7
	s_ashr_i32 s3, s2, 31
	s_lshl_b64 s[2:3], s[2:3], 1
	v_pk_mul_f32 v[108:109], v[112:113], v[108:109]
	v_pk_mul_f32 v[106:107], v[110:111], v[106:107]
	v_pk_mul_f32 v[100:101], v[104:105], v[100:101]
	v_pk_mul_f32 v[98:99], v[102:103], v[98:99]
	v_pk_mul_f32 v[92:93], v[96:97], v[92:93]
	v_pk_mul_f32 v[90:91], v[94:95], v[90:91]
	v_pk_mul_f32 v[84:85], v[88:89], v[84:85]
	v_pk_mul_f32 v[82:83], v[86:87], v[82:83]
	v_pk_mul_f32 v[76:77], v[80:81], v[76:77]
	v_pk_mul_f32 v[74:75], v[78:79], v[74:75]
	v_pk_mul_f32 v[68:69], v[72:73], v[68:69]
	v_pk_mul_f32 v[66:67], v[70:71], v[66:67]
	v_pk_mul_f32 v[60:61], v[64:65], v[60:61]
	v_pk_mul_f32 v[58:59], v[62:63], v[58:59]
	v_pk_mul_f32 v[52:53], v[56:57], v[52:53]
	v_pk_mul_f32 v[50:51], v[54:55], v[50:51]
	v_pk_mul_f32 v[44:45], v[48:49], v[44:45]
	v_pk_mul_f32 v[42:43], v[46:47], v[42:43]
	v_pk_mul_f32 v[36:37], v[40:41], v[36:37]
	v_pk_mul_f32 v[34:35], v[38:39], v[34:35]
	v_pk_mul_f32 v[28:29], v[32:33], v[28:29]
	v_pk_mul_f32 v[26:27], v[30:31], v[26:27]
	v_pk_mul_f32 v[20:21], v[24:25], v[20:21]
	v_pk_mul_f32 v[18:19], v[22:23], v[18:19]
	v_pk_mul_f32 v[12:13], v[16:17], v[12:13]
	v_pk_mul_f32 v[10:11], v[14:15], v[10:11]
	v_pk_mul_f32 v[4:5], v[8:9], v[4:5]
	v_pk_mul_f32 v[2:3], v[6:7], v[2:3]
	s_andn2_b64 vcc, exec, s[4:5]
	s_waitcnt lgkmcnt(0)
	v_mov_b32_e32 v202, v171
	v_mov_b32_e32 v203, v172
	v_mov_b32_e32 v171, v173
	v_pk_add_f32 v[170:171], v[202:203], v[170:171]
	v_mov_b32_e32 v172, v175
	v_mov_b32_e32 v173, v176
	v_mov_b32_e32 v175, v177
	v_mov_b32_e32 v176, v179
	v_mov_b32_e32 v177, v180
	v_mov_b32_e32 v179, v181
	v_add_f32_e32 v149, v170, v171
	v_pk_add_f32 v[170:171], v[172:173], v[174:175]
	v_pk_add_f32 v[172:173], v[176:177], v[178:179]
	v_fmamk_f32 v149, v149, 0x3a800000, v169
	v_add_f32_e32 v151, v170, v171
	v_add_f32_e32 v153, v172, v173
	v_rsq_f32_e32 v171, v149
	v_fmamk_f32 v149, v151, 0x3a800000, v169
	v_fmamk_f32 v151, v153, 0x3a800000, v169
	v_rsq_f32_e32 v173, v151
	v_mov_b32_e32 v180, v183
	v_mov_b32_e32 v181, v184
	v_mov_b32_e32 v183, v185
	v_mov_b32_e32 v184, v187
	v_mov_b32_e32 v185, v188
	v_mov_b32_e32 v187, v189
	v_pk_add_f32 v[174:175], v[180:181], v[182:183]
	v_pk_add_f32 v[176:177], v[184:185], v[186:187]
	v_mul_f32_e32 v172, 0xbfb8aa3b, v171
	v_add_f32_e32 v155, v174, v175
	v_add_f32_e32 v157, v176, v177
	v_pk_mul_f32 v[174:175], v[128:129], v[172:173] op_sel_hi:[1,0]
	v_pk_mul_f32 v[176:177], v[126:127], v[172:173] op_sel_hi:[1,0]
	v_exp_f32_e32 v174, v174
	v_exp_f32_e32 v176, v176
	v_exp_f32_e32 v175, v175
	v_exp_f32_e32 v177, v177
	v_mul_f32_e32 v170, v171, v171
	v_pk_mul_f32 v[122:123], v[122:123], v[170:171] op_sel_hi:[1,0]
	v_pk_add_f32 v[126:127], v[174:175], 1.0 op_sel_hi:[1,0]
	v_pk_add_f32 v[128:129], v[176:177], 1.0 op_sel_hi:[1,0]
	v_rcp_f32_e32 v126, v126
	v_rcp_f32_e32 v128, v128
	v_rcp_f32_e32 v127, v127
	v_rcp_f32_e32 v129, v129
	v_pk_mul_f32 v[124:125], v[124:125], v[170:171] op_sel_hi:[1,0]
	v_mov_b32_e32 v188, v191
	v_pk_mul_f32 v[124:125], v[124:125], v[126:127]
	v_pk_mul_f32 v[122:123], v[122:123], v[128:129]
	v_pk_mul_f32 v[126:127], v[120:121], v[172:173] op_sel_hi:[1,0]
	v_pk_mul_f32 v[128:129], v[118:119], v[172:173] op_sel_hi:[1,0]
	v_exp_f32_e32 v126, v126
	v_exp_f32_e32 v128, v128
	v_exp_f32_e32 v127, v127
	v_exp_f32_e32 v129, v129
	v_mov_b32_e32 v189, v192
	v_mov_b32_e32 v191, v193
	v_pk_add_f32 v[118:119], v[126:127], 1.0 op_sel_hi:[1,0]
	v_pk_add_f32 v[120:121], v[128:129], 1.0 op_sel_hi:[1,0]
	v_rcp_f32_e32 v118, v118
	v_rcp_f32_e32 v120, v120
	v_rcp_f32_e32 v119, v119
	v_rcp_f32_e32 v121, v121
	v_mov_b32_e32 v192, v195
	v_mov_b32_e32 v193, v196
	v_mov_b32_e32 v195, v197
	v_mov_b32_e32 v196, v199
	v_mov_b32_e32 v197, v200
	v_mov_b32_e32 v199, v201
	v_pk_add_f32 v[178:179], v[188:189], v[190:191]
	v_pk_add_f32 v[180:181], v[192:193], v[194:195]
	v_pk_add_f32 v[182:183], v[196:197], v[198:199]
	v_pk_mul_f32 v[114:115], v[114:115], v[170:171] op_sel_hi:[1,0]
	v_pk_mul_f32 v[116:117], v[116:117], v[170:171] op_sel_hi:[1,0]
	v_add_f32_e32 v159, v178, v179
	v_add_f32_e32 v161, v180, v181
	v_add_f32_e32 v163, v182, v183
	v_pk_mul_f32 v[126:127], v[116:117], v[118:119]
	v_pk_mul_f32 v[118:119], v[114:115], v[120:121]
	v_mov_b64_e32 v[114:115], s[12:13]
	v_fmamk_f32 v153, v155, 0x3a800000, v169
	v_fmamk_f32 v155, v157, 0x3a800000, v169
	v_fmamk_f32 v157, v159, 0x3a800000, v169
	v_fmamk_f32 v159, v161, 0x3a800000, v169
	v_fmamk_f32 v161, v163, 0x3a800000, v169
	v_rsq_f32_e32 v163, v149
	v_mad_i64_i32 v[116:117], s[0:1], v162, s46, v[114:115]
	v_lshl_add_u64 v[116:117], v[116:117], 0, s[2:3]
	v_lshl_add_u64 v[116:117], v[116:117], 0, s[8:9]
	v_lshl_add_u64 v[120:121], v[116:117], 0, v[138:139]
	v_cvt_pk_bf16_f32 v116, v122, v123
	v_cvt_pk_bf16_f32 v117, v124, v125
	v_cvt_pk_bf16_f32 v118, v118, v119
	v_cvt_pk_bf16_f32 v119, v126, v127
	global_store_dwordx4 v[120:121], v[116:119], off
	v_rsq_f32_e32 v153, v153
	v_rsq_f32_e32 v155, v155
	v_mul_f32_e32 v118, 0xbfb8aa3b, v163
	v_pk_mul_f32 v[120:121], v[112:113], v[118:119] op_sel_hi:[1,0]
	v_pk_mul_f32 v[122:123], v[110:111], v[118:119] op_sel_hi:[1,0]
	v_exp_f32_e32 v120, v120
	v_exp_f32_e32 v122, v122
	v_exp_f32_e32 v121, v121
	v_exp_f32_e32 v123, v123
	v_mul_f32_e32 v116, v163, v163
	v_pk_mul_f32 v[106:107], v[106:107], v[116:117] op_sel_hi:[1,0]
	v_pk_add_f32 v[110:111], v[120:121], 1.0 op_sel_hi:[1,0]
	v_pk_add_f32 v[112:113], v[122:123], 1.0 op_sel_hi:[1,0]
	v_rcp_f32_e32 v110, v110
	v_rcp_f32_e32 v112, v112
	v_rcp_f32_e32 v111, v111
	v_rcp_f32_e32 v113, v113
	v_pk_mul_f32 v[108:109], v[108:109], v[116:117] op_sel_hi:[1,0]
	v_pk_mul_f32 v[98:99], v[98:99], v[116:117] op_sel_hi:[1,0]
	v_pk_mul_f32 v[108:109], v[108:109], v[110:111]
	v_pk_mul_f32 v[106:107], v[106:107], v[112:113]
	v_pk_mul_f32 v[110:111], v[104:105], v[118:119] op_sel_hi:[1,0]
	v_pk_mul_f32 v[112:113], v[102:103], v[118:119] op_sel_hi:[1,0]
	v_exp_f32_e32 v110, v110
	v_exp_f32_e32 v112, v112
	v_exp_f32_e32 v111, v111
	v_exp_f32_e32 v113, v113
	v_pk_mul_f32 v[100:101], v[100:101], v[116:117] op_sel_hi:[1,0]
	v_rsq_f32_e32 v157, v157
	v_pk_add_f32 v[102:103], v[110:111], 1.0 op_sel_hi:[1,0]
	v_pk_add_f32 v[104:105], v[112:113], 1.0 op_sel_hi:[1,0]
	v_rcp_f32_e32 v102, v102
	v_rcp_f32_e32 v104, v104
	v_rcp_f32_e32 v103, v103
	v_rcp_f32_e32 v105, v105
	v_rsq_f32_e32 v151, v159
	v_rsq_f32_e32 v149, v161
	v_pk_mul_f32 v[102:103], v[100:101], v[102:103]
	v_pk_mul_f32 v[100:101], v[98:99], v[104:105]
	v_mad_i64_i32 v[98:99], s[0:1], v160, s46, v[114:115]
	v_lshl_add_u64 v[98:99], v[98:99], 0, s[2:3]
	v_lshl_add_u64 v[98:99], v[98:99], 0, s[8:9]
	v_lshl_add_u64 v[104:105], v[98:99], 0, v[138:139]
	v_cvt_pk_bf16_f32 v98, v106, v107
	v_cvt_pk_bf16_f32 v99, v108, v109
	v_cvt_pk_bf16_f32 v100, v100, v101
	v_cvt_pk_bf16_f32 v101, v102, v103
	global_store_dwordx4 v[104:105], v[98:101], off
	s_nop 1
	v_mul_f32_e32 v100, 0xbfb8aa3b, v173
	v_pk_mul_f32 v[102:103], v[96:97], v[100:101] op_sel_hi:[1,0]
	v_pk_mul_f32 v[104:105], v[94:95], v[100:101] op_sel_hi:[1,0]
	v_exp_f32_e32 v102, v102
	v_exp_f32_e32 v104, v104
	v_exp_f32_e32 v103, v103
	v_exp_f32_e32 v105, v105
	v_mul_f32_e32 v98, v173, v173
	v_pk_mul_f32 v[90:91], v[90:91], v[98:99] op_sel_hi:[1,0]
	v_pk_add_f32 v[94:95], v[102:103], 1.0 op_sel_hi:[1,0]
	v_pk_add_f32 v[96:97], v[104:105], 1.0 op_sel_hi:[1,0]
	v_rcp_f32_e32 v94, v94
	v_rcp_f32_e32 v96, v96
	v_rcp_f32_e32 v95, v95
	v_rcp_f32_e32 v97, v97
	v_pk_mul_f32 v[92:93], v[92:93], v[98:99] op_sel_hi:[1,0]
	v_pk_mul_f32 v[82:83], v[82:83], v[98:99] op_sel_hi:[1,0]
	v_pk_mul_f32 v[92:93], v[92:93], v[94:95]
	v_pk_mul_f32 v[90:91], v[90:91], v[96:97]
	v_pk_mul_f32 v[94:95], v[88:89], v[100:101] op_sel_hi:[1,0]
	v_pk_mul_f32 v[96:97], v[86:87], v[100:101] op_sel_hi:[1,0]
	v_exp_f32_e32 v94, v94
	v_exp_f32_e32 v96, v96
	v_exp_f32_e32 v95, v95
	v_exp_f32_e32 v97, v97
	v_pk_mul_f32 v[84:85], v[84:85], v[98:99] op_sel_hi:[1,0]
	v_pk_add_f32 v[86:87], v[94:95], 1.0 op_sel_hi:[1,0]
	v_pk_add_f32 v[88:89], v[96:97], 1.0 op_sel_hi:[1,0]
	v_rcp_f32_e32 v86, v86
	v_rcp_f32_e32 v88, v88
	v_rcp_f32_e32 v87, v87
	v_rcp_f32_e32 v89, v89
	v_pk_mul_f32 v[86:87], v[84:85], v[86:87]
	v_pk_mul_f32 v[84:85], v[82:83], v[88:89]
	v_mad_i64_i32 v[82:83], s[0:1], v158, s46, v[114:115]
	v_lshl_add_u64 v[82:83], v[82:83], 0, s[2:3]
	v_lshl_add_u64 v[82:83], v[82:83], 0, s[8:9]
	v_lshl_add_u64 v[88:89], v[82:83], 0, v[138:139]
	v_cvt_pk_bf16_f32 v82, v90, v91
	v_cvt_pk_bf16_f32 v83, v92, v93
	v_cvt_pk_bf16_f32 v84, v84, v85
	v_cvt_pk_bf16_f32 v85, v86, v87
	global_store_dwordx4 v[88:89], v[82:85], off
	s_nop 1
	v_mul_f32_e32 v84, 0xbfb8aa3b, v153
	v_pk_mul_f32 v[86:87], v[80:81], v[84:85] op_sel_hi:[1,0]
	v_pk_mul_f32 v[88:89], v[78:79], v[84:85] op_sel_hi:[1,0]
	v_exp_f32_e32 v86, v86
	v_exp_f32_e32 v88, v88
	v_exp_f32_e32 v87, v87
	v_exp_f32_e32 v89, v89
	v_mul_f32_e32 v82, v153, v153
	v_pk_mul_f32 v[74:75], v[74:75], v[82:83] op_sel_hi:[1,0]
	v_pk_add_f32 v[78:79], v[86:87], 1.0 op_sel_hi:[1,0]
	v_pk_add_f32 v[80:81], v[88:89], 1.0 op_sel_hi:[1,0]
	v_rcp_f32_e32 v78, v78
	v_rcp_f32_e32 v80, v80
	v_rcp_f32_e32 v79, v79
	v_rcp_f32_e32 v81, v81
	v_pk_mul_f32 v[76:77], v[76:77], v[82:83] op_sel_hi:[1,0]
	v_pk_mul_f32 v[66:67], v[66:67], v[82:83] op_sel_hi:[1,0]
	v_pk_mul_f32 v[76:77], v[76:77], v[78:79]
	v_pk_mul_f32 v[74:75], v[74:75], v[80:81]
	v_pk_mul_f32 v[78:79], v[72:73], v[84:85] op_sel_hi:[1,0]
	v_pk_mul_f32 v[80:81], v[70:71], v[84:85] op_sel_hi:[1,0]
	v_exp_f32_e32 v78, v78
	v_exp_f32_e32 v80, v80
	v_exp_f32_e32 v79, v79
	v_exp_f32_e32 v81, v81
	v_pk_mul_f32 v[68:69], v[68:69], v[82:83] op_sel_hi:[1,0]
	v_pk_add_f32 v[70:71], v[78:79], 1.0 op_sel_hi:[1,0]
	v_pk_add_f32 v[72:73], v[80:81], 1.0 op_sel_hi:[1,0]
	v_rcp_f32_e32 v70, v70
	v_rcp_f32_e32 v72, v72
	v_rcp_f32_e32 v71, v71
	v_rcp_f32_e32 v73, v73
	v_pk_mul_f32 v[70:71], v[68:69], v[70:71]
	v_pk_mul_f32 v[68:69], v[66:67], v[72:73]
	v_mad_i64_i32 v[66:67], s[0:1], v156, s46, v[114:115]
	v_lshl_add_u64 v[66:67], v[66:67], 0, s[2:3]
	v_lshl_add_u64 v[66:67], v[66:67], 0, s[8:9]
	v_lshl_add_u64 v[72:73], v[66:67], 0, v[138:139]
	v_cvt_pk_bf16_f32 v66, v74, v75
	v_cvt_pk_bf16_f32 v67, v76, v77
	v_cvt_pk_bf16_f32 v68, v68, v69
	v_cvt_pk_bf16_f32 v69, v70, v71
	global_store_dwordx4 v[72:73], v[66:69], off
	s_nop 1
	v_mul_f32_e32 v68, 0xbfb8aa3b, v155
	v_pk_mul_f32 v[70:71], v[64:65], v[68:69] op_sel_hi:[1,0]
	v_pk_mul_f32 v[72:73], v[62:63], v[68:69] op_sel_hi:[1,0]
	v_exp_f32_e32 v70, v70
	v_exp_f32_e32 v72, v72
	v_exp_f32_e32 v71, v71
	v_exp_f32_e32 v73, v73
	v_mul_f32_e32 v66, v155, v155
	v_pk_mul_f32 v[58:59], v[58:59], v[66:67] op_sel_hi:[1,0]
	v_pk_add_f32 v[62:63], v[70:71], 1.0 op_sel_hi:[1,0]
	v_pk_add_f32 v[64:65], v[72:73], 1.0 op_sel_hi:[1,0]
	v_rcp_f32_e32 v62, v62
	v_rcp_f32_e32 v64, v64
	v_rcp_f32_e32 v63, v63
	v_rcp_f32_e32 v65, v65
	v_pk_mul_f32 v[60:61], v[60:61], v[66:67] op_sel_hi:[1,0]
	v_pk_mul_f32 v[50:51], v[50:51], v[66:67] op_sel_hi:[1,0]
	v_pk_mul_f32 v[60:61], v[60:61], v[62:63]
	v_pk_mul_f32 v[58:59], v[58:59], v[64:65]
	v_pk_mul_f32 v[62:63], v[56:57], v[68:69] op_sel_hi:[1,0]
	v_pk_mul_f32 v[64:65], v[54:55], v[68:69] op_sel_hi:[1,0]
	v_exp_f32_e32 v62, v62
	v_exp_f32_e32 v64, v64
	v_exp_f32_e32 v63, v63
	v_exp_f32_e32 v65, v65
	v_pk_mul_f32 v[52:53], v[52:53], v[66:67] op_sel_hi:[1,0]
	v_pk_add_f32 v[54:55], v[62:63], 1.0 op_sel_hi:[1,0]
	v_pk_add_f32 v[56:57], v[64:65], 1.0 op_sel_hi:[1,0]
	v_rcp_f32_e32 v54, v54
	v_rcp_f32_e32 v56, v56
	v_rcp_f32_e32 v55, v55
	v_rcp_f32_e32 v57, v57
	v_pk_mul_f32 v[54:55], v[52:53], v[54:55]
	v_pk_mul_f32 v[52:53], v[50:51], v[56:57]
	v_mad_i64_i32 v[50:51], s[0:1], v154, s46, v[114:115]
	v_lshl_add_u64 v[50:51], v[50:51], 0, s[2:3]
	v_lshl_add_u64 v[50:51], v[50:51], 0, s[8:9]
	v_lshl_add_u64 v[56:57], v[50:51], 0, v[138:139]
	v_cvt_pk_bf16_f32 v50, v58, v59
	v_cvt_pk_bf16_f32 v51, v60, v61
	v_cvt_pk_bf16_f32 v52, v52, v53
	v_cvt_pk_bf16_f32 v53, v54, v55
	global_store_dwordx4 v[56:57], v[50:53], off
	s_nop 1
	v_mul_f32_e32 v52, 0xbfb8aa3b, v157
	v_pk_mul_f32 v[54:55], v[48:49], v[52:53] op_sel_hi:[1,0]
	v_pk_mul_f32 v[56:57], v[46:47], v[52:53] op_sel_hi:[1,0]
	v_exp_f32_e32 v54, v54
	v_exp_f32_e32 v56, v56
	v_exp_f32_e32 v55, v55
	v_exp_f32_e32 v57, v57
	v_mul_f32_e32 v50, v157, v157
	v_pk_mul_f32 v[42:43], v[42:43], v[50:51] op_sel_hi:[1,0]
	v_pk_add_f32 v[46:47], v[54:55], 1.0 op_sel_hi:[1,0]
	v_pk_add_f32 v[48:49], v[56:57], 1.0 op_sel_hi:[1,0]
	v_rcp_f32_e32 v46, v46
	v_rcp_f32_e32 v48, v48
	v_rcp_f32_e32 v47, v47
	v_rcp_f32_e32 v49, v49
	v_pk_mul_f32 v[44:45], v[44:45], v[50:51] op_sel_hi:[1,0]
	v_pk_mul_f32 v[34:35], v[34:35], v[50:51] op_sel_hi:[1,0]
	v_pk_mul_f32 v[44:45], v[44:45], v[46:47]
	v_pk_mul_f32 v[42:43], v[42:43], v[48:49]
	v_pk_mul_f32 v[46:47], v[40:41], v[52:53] op_sel_hi:[1,0]
	v_pk_mul_f32 v[48:49], v[38:39], v[52:53] op_sel_hi:[1,0]
	v_exp_f32_e32 v46, v46
	v_exp_f32_e32 v48, v48
	v_exp_f32_e32 v47, v47
	v_exp_f32_e32 v49, v49
	v_pk_mul_f32 v[36:37], v[36:37], v[50:51] op_sel_hi:[1,0]
	v_pk_add_f32 v[38:39], v[46:47], 1.0 op_sel_hi:[1,0]
	v_pk_add_f32 v[40:41], v[48:49], 1.0 op_sel_hi:[1,0]
	v_rcp_f32_e32 v38, v38
	v_rcp_f32_e32 v40, v40
	v_rcp_f32_e32 v39, v39
	v_rcp_f32_e32 v41, v41
	v_pk_mul_f32 v[38:39], v[36:37], v[38:39]
	v_pk_mul_f32 v[36:37], v[34:35], v[40:41]
	v_mad_i64_i32 v[34:35], s[0:1], v152, s46, v[114:115]
	v_lshl_add_u64 v[34:35], v[34:35], 0, s[2:3]
	v_lshl_add_u64 v[34:35], v[34:35], 0, s[8:9]
	v_lshl_add_u64 v[40:41], v[34:35], 0, v[138:139]
	v_cvt_pk_bf16_f32 v34, v42, v43
	v_cvt_pk_bf16_f32 v35, v44, v45
	v_cvt_pk_bf16_f32 v36, v36, v37
	v_cvt_pk_bf16_f32 v37, v38, v39
	global_store_dwordx4 v[40:41], v[34:37], off
	s_nop 1
	v_mul_f32_e32 v36, 0xbfb8aa3b, v151
	v_pk_mul_f32 v[38:39], v[32:33], v[36:37] op_sel_hi:[1,0]
	v_pk_mul_f32 v[40:41], v[30:31], v[36:37] op_sel_hi:[1,0]
	v_exp_f32_e32 v38, v38
	v_exp_f32_e32 v40, v40
	v_exp_f32_e32 v39, v39
	v_exp_f32_e32 v41, v41
	v_mul_f32_e32 v34, v151, v151
	v_pk_mul_f32 v[26:27], v[26:27], v[34:35] op_sel_hi:[1,0]
	v_pk_add_f32 v[30:31], v[38:39], 1.0 op_sel_hi:[1,0]
	v_pk_add_f32 v[32:33], v[40:41], 1.0 op_sel_hi:[1,0]
	v_rcp_f32_e32 v30, v30
	v_rcp_f32_e32 v32, v32
	v_rcp_f32_e32 v31, v31
	v_rcp_f32_e32 v33, v33
	v_pk_mul_f32 v[28:29], v[28:29], v[34:35] op_sel_hi:[1,0]
	v_pk_mul_f32 v[18:19], v[18:19], v[34:35] op_sel_hi:[1,0]
	v_pk_mul_f32 v[28:29], v[28:29], v[30:31]
	v_pk_mul_f32 v[26:27], v[26:27], v[32:33]
	v_pk_mul_f32 v[30:31], v[24:25], v[36:37] op_sel_hi:[1,0]
	v_pk_mul_f32 v[32:33], v[22:23], v[36:37] op_sel_hi:[1,0]
	v_exp_f32_e32 v30, v30
	v_exp_f32_e32 v32, v32
	v_exp_f32_e32 v31, v31
	v_exp_f32_e32 v33, v33
	v_pk_mul_f32 v[20:21], v[20:21], v[34:35] op_sel_hi:[1,0]
	v_pk_add_f32 v[22:23], v[30:31], 1.0 op_sel_hi:[1,0]
	v_pk_add_f32 v[24:25], v[32:33], 1.0 op_sel_hi:[1,0]
	v_rcp_f32_e32 v22, v22
	v_rcp_f32_e32 v24, v24
	v_rcp_f32_e32 v23, v23
	v_rcp_f32_e32 v25, v25
	v_pk_mul_f32 v[22:23], v[20:21], v[22:23]
	v_pk_mul_f32 v[20:21], v[18:19], v[24:25]
	v_mad_i64_i32 v[18:19], s[0:1], v150, s46, v[114:115]
	v_lshl_add_u64 v[18:19], v[18:19], 0, s[2:3]
	v_lshl_add_u64 v[18:19], v[18:19], 0, s[8:9]
	v_lshl_add_u64 v[24:25], v[18:19], 0, v[138:139]
	v_cvt_pk_bf16_f32 v18, v26, v27
	v_cvt_pk_bf16_f32 v19, v28, v29
	v_cvt_pk_bf16_f32 v20, v20, v21
	v_cvt_pk_bf16_f32 v21, v22, v23
	global_store_dwordx4 v[24:25], v[18:21], off
	s_nop 1
	v_mul_f32_e32 v20, 0xbfb8aa3b, v149
	v_pk_mul_f32 v[22:23], v[16:17], v[20:21] op_sel_hi:[1,0]
	v_pk_mul_f32 v[24:25], v[14:15], v[20:21] op_sel_hi:[1,0]
	v_exp_f32_e32 v22, v22
	v_exp_f32_e32 v24, v24
	v_exp_f32_e32 v23, v23
	v_exp_f32_e32 v25, v25
	v_mul_f32_e32 v18, v149, v149
	v_pk_mul_f32 v[10:11], v[10:11], v[18:19] op_sel_hi:[1,0]
	v_pk_add_f32 v[14:15], v[22:23], 1.0 op_sel_hi:[1,0]
	v_pk_add_f32 v[16:17], v[24:25], 1.0 op_sel_hi:[1,0]
	v_rcp_f32_e32 v14, v14
	v_rcp_f32_e32 v16, v16
	v_rcp_f32_e32 v15, v15
	v_rcp_f32_e32 v17, v17
	v_pk_mul_f32 v[12:13], v[12:13], v[18:19] op_sel_hi:[1,0]
	v_pk_mul_f32 v[2:3], v[2:3], v[18:19] op_sel_hi:[1,0]
	v_pk_mul_f32 v[12:13], v[12:13], v[14:15]
	v_pk_mul_f32 v[10:11], v[10:11], v[16:17]
	v_pk_mul_f32 v[14:15], v[8:9], v[20:21] op_sel_hi:[1,0]
	v_pk_mul_f32 v[16:17], v[6:7], v[20:21] op_sel_hi:[1,0]
	v_exp_f32_e32 v14, v14
	v_exp_f32_e32 v16, v16
	v_exp_f32_e32 v15, v15
	v_exp_f32_e32 v17, v17
	v_pk_mul_f32 v[4:5], v[4:5], v[18:19] op_sel_hi:[1,0]
	v_pk_add_f32 v[6:7], v[14:15], 1.0 op_sel_hi:[1,0]
	v_pk_add_f32 v[8:9], v[16:17], 1.0 op_sel_hi:[1,0]
	v_rcp_f32_e32 v6, v6
	v_rcp_f32_e32 v8, v8
	v_rcp_f32_e32 v7, v7
	v_rcp_f32_e32 v9, v9
	v_pk_mul_f32 v[6:7], v[4:5], v[6:7]
	v_pk_mul_f32 v[4:5], v[2:3], v[8:9]
	v_mad_i64_i32 v[2:3], s[0:1], v148, s46, v[114:115]
	v_lshl_add_u64 v[2:3], v[2:3], 0, s[2:3]
	v_lshl_add_u64 v[2:3], v[2:3], 0, s[8:9]
	v_lshl_add_u64 v[8:9], v[2:3], 0, v[138:139]
	s_mov_b64 s[2:3], -1
	v_cvt_pk_bf16_f32 v2, v10, v11
	v_cvt_pk_bf16_f32 v3, v12, v13
	v_cvt_pk_bf16_f32 v4, v4, v5
	v_cvt_pk_bf16_f32 v5, v6, v7
	global_store_dwordx4 v[8:9], v[2:5], off
	s_cbranch_vccnz .LBB0_1711
	s_andn2_b64 vcc, exec, s[10:11]
	s_cbranch_vccnz .LBB0_1710
	s_barrier
	s_branch .LBB0_1710

.LBB0_1941:
	v_lshl_add_u32 v198, s26, 8, v1
	s_and_b32 s99, s45, 1
	s_lshl_b32 s99, s99, 12
	s_add_i32 s99, s99, 0x21000
	v_lshl_add_u32 v252, v1, 4, s99
	v_ashrrev_i32_e32 v199, 31, v198
	v_or_b32_e32 v200, 16, v198
	v_or_b32_e32 v158, 32, v198
	v_lshl_add_u64 v[148:149], v[198:199], 4, s[76:77]
	v_ashrrev_i32_e32 v201, 31, v200
	v_ashrrev_i32_e32 v159, 31, v158
	v_or_b32_e32 v156, 48, v198
	v_lshl_add_u64 v[150:151], v[200:201], 4, s[76:77]
	ds_read_b128 v[166:169], v252
	ds_read_b128 v[170:173], v252 offset:256
	v_lshl_add_u64 v[148:149], v[158:159], 4, s[76:77]
	v_ashrrev_i32_e32 v157, 31, v156
	v_lshl_add_u64 v[150:151], v[156:157], 4, s[76:77]
	ds_read_b128 v[174:177], v252 offset:512
	ds_read_b128 v[178:181], v252 offset:768
	v_add_u32_e32 v154, 0x80, v198
	v_ashrrev_i32_e32 v155, 31, v154
	v_add_u32_e32 v152, 0x90, v198
	v_lshl_add_u64 v[148:149], v[154:155], 4, s[76:77]
	v_ashrrev_i32_e32 v153, 31, v152
	v_lshl_add_u64 v[150:151], v[152:153], 4, s[76:77]
	ds_read_b128 v[182:185], v252 offset:2048
	ds_read_b128 v[186:189], v252 offset:2304
	v_add_u32_e32 v150, 0xa0, v198
	v_ashrrev_i32_e32 v151, 31, v150
	v_lshl_add_u64 v[148:149], v[150:151], 4, s[76:77]
	ds_read_b128 v[190:193], v252 offset:2560
	v_add_u32_e32 v148, 0xb0, v198
	v_ashrrev_i32_e32 v149, 31, v148
	v_lshl_add_u64 v[194:195], v[148:149], 4, s[76:77]
	ds_read_b128 v[194:197], v252 offset:2816
	v_pk_mul_f32 v[122:123], v[126:127], v[122:123]
	v_pk_mul_f32 v[124:125], v[128:129], v[124:125]
	v_pk_mul_f32 v[116:117], v[120:121], v[116:117]
	v_pk_mul_f32 v[114:115], v[118:119], v[114:115]
	s_lshl_b32 s0, s46, 7
	s_ashr_i32 s1, s0, 31
	s_lshl_b64 s[2:3], s[0:1], 1
	v_pk_mul_f32 v[100:101], v[108:109], v[100:101]
	v_pk_mul_f32 v[98:99], v[106:107], v[98:99]
	v_pk_mul_f32 v[102:103], v[110:111], v[102:103]
	v_pk_mul_f32 v[104:105], v[112:113], v[104:105]
	v_pk_mul_f32 v[84:85], v[92:93], v[84:85]
	v_pk_mul_f32 v[82:83], v[90:91], v[82:83]
	v_pk_mul_f32 v[86:87], v[94:95], v[86:87]
	v_pk_mul_f32 v[88:89], v[96:97], v[88:89]
	v_pk_mul_f32 v[68:69], v[76:77], v[68:69]
	v_pk_mul_f32 v[66:67], v[74:75], v[66:67]
	v_pk_mul_f32 v[70:71], v[78:79], v[70:71]
	v_pk_mul_f32 v[72:73], v[80:81], v[72:73]
	v_pk_mul_f32 v[52:53], v[60:61], v[52:53]
	v_pk_mul_f32 v[50:51], v[58:59], v[50:51]
	v_pk_mul_f32 v[54:55], v[62:63], v[54:55]
	v_pk_mul_f32 v[56:57], v[64:65], v[56:57]
	v_pk_mul_f32 v[36:37], v[44:45], v[36:37]
	v_pk_mul_f32 v[34:35], v[42:43], v[34:35]
	v_pk_mul_f32 v[38:39], v[46:47], v[38:39]
	v_pk_mul_f32 v[40:41], v[48:49], v[40:41]
	v_pk_mul_f32 v[20:21], v[28:29], v[20:21]
	v_pk_mul_f32 v[18:19], v[26:27], v[18:19]
	v_pk_mul_f32 v[22:23], v[30:31], v[22:23]
	v_pk_mul_f32 v[24:25], v[32:33], v[24:25]
	v_pk_mul_f32 v[4:5], v[12:13], v[4:5]
	v_pk_mul_f32 v[2:3], v[10:11], v[2:3]
	v_pk_mul_f32 v[8:9], v[16:17], v[8:9]
	v_pk_mul_f32 v[6:7], v[14:15], v[6:7]
	s_andn2_b64 vcc, exec, s[4:5]
	s_waitcnt lgkmcnt(0)
	v_mov_b32_e32 v126, v167
	v_mov_b32_e32 v127, v168
	v_mov_b32_e32 v167, v169
	v_pk_add_f32 v[126:127], v[126:127], v[166:167]
	v_mov_b32_e32 v128, v171
	v_mov_b32_e32 v129, v172
	v_mov_b32_e32 v171, v173
	v_mov_b32_e32 v166, v175
	v_mov_b32_e32 v167, v176
	v_mov_b32_e32 v175, v177
	v_add_f32_e32 v165, v126, v127
	v_pk_add_f32 v[126:127], v[128:129], v[170:171]
	v_pk_add_f32 v[128:129], v[166:167], v[174:175]
	v_fmamk_f32 v165, v165, 0x3a800000, v164
	v_add_f32_e32 v126, v126, v127
	v_add_f32_e32 v127, v128, v129
	v_rsq_f32_e32 v165, v165
	v_fmamk_f32 v127, v127, 0x3a800000, v164
	v_rsq_f32_e32 v127, v127
	v_mov_b32_e32 v168, v179
	v_mov_b32_e32 v169, v180
	v_mov_b32_e32 v179, v181
	v_mov_b32_e32 v172, v183
	v_mov_b32_e32 v173, v184
	v_mov_b32_e32 v183, v185
	v_pk_add_f32 v[166:167], v[168:169], v[178:179]
	v_pk_add_f32 v[168:169], v[172:173], v[182:183]
	v_fmamk_f32 v126, v126, 0x3a800000, v164
	v_add_f32_e32 v129, v168, v169
	v_rsq_f32_e32 v169, v126
	v_mul_f32_e32 v126, v165, v165
	v_pk_mul_f32 v[118:119], v[116:117], v[126:127] op_sel_hi:[1,0]
	v_pk_mul_f32 v[116:117], v[114:115], v[126:127] op_sel_hi:[1,0]
	v_lshlrev_b64 v[114:115], 11, v[198:199]
	v_lshl_add_u64 v[114:115], s[12:13], 0, v[114:115]
	v_lshl_add_u64 v[114:115], v[114:115], 0, s[2:3]
	v_lshl_add_u64 v[114:115], v[114:115], 0, s[8:9]
	v_pk_mul_f32 v[122:123], v[122:123], v[126:127] op_sel_hi:[1,0]
	v_lshl_add_u64 v[120:121], v[114:115], 0, v[138:139]
	v_cvt_pk_bf16_f32 v114, v122, v123
	v_pk_mul_f32 v[124:125], v[124:125], v[126:127] op_sel_hi:[1,0]
	v_add_f32_e32 v128, v166, v167
	v_cvt_pk_bf16_f32 v115, v124, v125
	v_cvt_pk_bf16_f32 v116, v116, v117
	v_cvt_pk_bf16_f32 v117, v118, v119
	global_store_dwordx4 v[120:121], v[114:117], off
	v_fmamk_f32 v128, v128, 0x3a800000, v164
	v_rsq_f32_e32 v128, v128
	v_mul_f32_e32 v114, v169, v169
	v_pk_mul_f32 v[106:107], v[100:101], v[114:115] op_sel_hi:[1,0]
	v_pk_mul_f32 v[100:101], v[98:99], v[114:115] op_sel_hi:[1,0]
	v_lshlrev_b64 v[98:99], 11, v[200:201]
	v_lshl_add_u64 v[98:99], s[12:13], 0, v[98:99]
	v_lshl_add_u64 v[98:99], v[98:99], 0, s[2:3]
	v_lshl_add_u64 v[98:99], v[98:99], 0, s[8:9]
	v_pk_mul_f32 v[102:103], v[102:103], v[114:115] op_sel_hi:[1,0]
	v_lshl_add_u64 v[108:109], v[98:99], 0, v[138:139]
	v_cvt_pk_bf16_f32 v98, v102, v103
	v_pk_mul_f32 v[104:105], v[104:105], v[114:115] op_sel_hi:[1,0]
	v_fmamk_f32 v129, v129, 0x3a800000, v164
	v_cvt_pk_bf16_f32 v99, v104, v105
	v_cvt_pk_bf16_f32 v100, v100, v101
	v_cvt_pk_bf16_f32 v101, v106, v107
	global_store_dwordx4 v[108:109], v[98:101], off
	v_rsq_f32_e32 v129, v129
	v_mov_b32_e32 v176, v187
	v_mul_f32_e32 v98, v127, v127
	v_pk_mul_f32 v[90:91], v[84:85], v[98:99] op_sel_hi:[1,0]
	v_pk_mul_f32 v[84:85], v[82:83], v[98:99] op_sel_hi:[1,0]
	v_lshlrev_b64 v[82:83], 11, v[158:159]
	v_lshl_add_u64 v[82:83], s[12:13], 0, v[82:83]
	v_lshl_add_u64 v[82:83], v[82:83], 0, s[2:3]
	v_lshl_add_u64 v[82:83], v[82:83], 0, s[8:9]
	v_pk_mul_f32 v[86:87], v[86:87], v[98:99] op_sel_hi:[1,0]
	v_lshl_add_u64 v[92:93], v[82:83], 0, v[138:139]
	v_cvt_pk_bf16_f32 v82, v86, v87
	v_pk_mul_f32 v[88:89], v[88:89], v[98:99] op_sel_hi:[1,0]
	v_mov_b32_e32 v177, v188
	v_cvt_pk_bf16_f32 v83, v88, v89
	v_cvt_pk_bf16_f32 v84, v84, v85
	v_cvt_pk_bf16_f32 v85, v90, v91
	global_store_dwordx4 v[92:93], v[82:85], off
	v_mov_b32_e32 v187, v189
	v_pk_add_f32 v[170:171], v[176:177], v[186:187]
	v_mul_f32_e32 v82, v128, v128
	v_pk_mul_f32 v[74:75], v[68:69], v[82:83] op_sel_hi:[1,0]
	v_pk_mul_f32 v[68:69], v[66:67], v[82:83] op_sel_hi:[1,0]
	v_lshlrev_b64 v[66:67], 11, v[156:157]
	v_lshl_add_u64 v[66:67], s[12:13], 0, v[66:67]
	v_lshl_add_u64 v[66:67], v[66:67], 0, s[2:3]
	v_lshl_add_u64 v[66:67], v[66:67], 0, s[8:9]
	v_pk_mul_f32 v[70:71], v[70:71], v[82:83] op_sel_hi:[1,0]
	v_lshl_add_u64 v[76:77], v[66:67], 0, v[138:139]
	v_cvt_pk_bf16_f32 v66, v70, v71
	v_add_f32_e32 v166, v170, v171
	v_pk_mul_f32 v[72:73], v[72:73], v[82:83] op_sel_hi:[1,0]
	v_fmamk_f32 v166, v166, 0x3a800000, v164
	v_cvt_pk_bf16_f32 v67, v72, v73
	v_cvt_pk_bf16_f32 v68, v68, v69
	v_cvt_pk_bf16_f32 v69, v74, v75
	global_store_dwordx4 v[76:77], v[66:69], off
	v_rsq_f32_e32 v166, v166
	v_mov_b32_e32 v180, v191
	v_mul_f32_e32 v66, v129, v129
	v_pk_mul_f32 v[58:59], v[52:53], v[66:67] op_sel_hi:[1,0]
	v_pk_mul_f32 v[52:53], v[50:51], v[66:67] op_sel_hi:[1,0]
	v_lshlrev_b64 v[50:51], 11, v[154:155]
	v_lshl_add_u64 v[50:51], s[12:13], 0, v[50:51]
	v_lshl_add_u64 v[50:51], v[50:51], 0, s[2:3]
	v_mov_b32_e32 v181, v192
	v_mov_b32_e32 v191, v193
	v_lshl_add_u64 v[50:51], v[50:51], 0, s[8:9]
	v_pk_add_f32 v[172:173], v[180:181], v[190:191]
	v_pk_mul_f32 v[54:55], v[54:55], v[66:67] op_sel_hi:[1,0]
	v_lshl_add_u64 v[60:61], v[50:51], 0, v[138:139]
	v_cvt_pk_bf16_f32 v50, v54, v55
	v_add_f32_e32 v167, v172, v173
	v_pk_mul_f32 v[56:57], v[56:57], v[66:67] op_sel_hi:[1,0]
	v_fmamk_f32 v167, v167, 0x3a800000, v164
	v_cvt_pk_bf16_f32 v51, v56, v57
	v_cvt_pk_bf16_f32 v52, v52, v53
	v_cvt_pk_bf16_f32 v53, v58, v59
	global_store_dwordx4 v[60:61], v[50:53], off
	v_rsq_f32_e32 v167, v167
	v_mov_b32_e32 v184, v195
	v_mul_f32_e32 v50, v166, v166
	v_pk_mul_f32 v[42:43], v[36:37], v[50:51] op_sel_hi:[1,0]
	v_pk_mul_f32 v[36:37], v[34:35], v[50:51] op_sel_hi:[1,0]
	v_lshlrev_b64 v[34:35], 11, v[152:153]
	v_lshl_add_u64 v[34:35], s[12:13], 0, v[34:35]
	v_lshl_add_u64 v[34:35], v[34:35], 0, s[2:3]
	v_mov_b32_e32 v185, v196
	v_mov_b32_e32 v195, v197
	v_lshl_add_u64 v[34:35], v[34:35], 0, s[8:9]
	v_pk_add_f32 v[174:175], v[184:185], v[194:195]
	v_pk_mul_f32 v[38:39], v[38:39], v[50:51] op_sel_hi:[1,0]
	v_lshl_add_u64 v[44:45], v[34:35], 0, v[138:139]
	v_cvt_pk_bf16_f32 v34, v38, v39
	v_add_f32_e32 v168, v174, v175
	v_pk_mul_f32 v[40:41], v[40:41], v[50:51] op_sel_hi:[1,0]
	v_fmamk_f32 v168, v168, 0x3a800000, v164
	v_cvt_pk_bf16_f32 v35, v40, v41
	v_cvt_pk_bf16_f32 v36, v36, v37
	v_cvt_pk_bf16_f32 v37, v42, v43
	global_store_dwordx4 v[44:45], v[34:37], off
	v_rsq_f32_e32 v168, v168
	s_nop 0
	v_mul_f32_e32 v34, v167, v167
	v_pk_mul_f32 v[26:27], v[20:21], v[34:35] op_sel_hi:[1,0]
	v_pk_mul_f32 v[20:21], v[18:19], v[34:35] op_sel_hi:[1,0]
	v_lshlrev_b64 v[18:19], 11, v[150:151]
	v_lshl_add_u64 v[18:19], s[12:13], 0, v[18:19]
	v_lshl_add_u64 v[18:19], v[18:19], 0, s[2:3]
	v_lshl_add_u64 v[18:19], v[18:19], 0, s[8:9]
	v_pk_mul_f32 v[22:23], v[22:23], v[34:35] op_sel_hi:[1,0]
	v_lshl_add_u64 v[28:29], v[18:19], 0, v[138:139]
	v_cvt_pk_bf16_f32 v18, v22, v23
	v_pk_mul_f32 v[24:25], v[24:25], v[34:35] op_sel_hi:[1,0]
	s_nop 0
	v_cvt_pk_bf16_f32 v19, v24, v25
	v_cvt_pk_bf16_f32 v20, v20, v21
	v_cvt_pk_bf16_f32 v21, v26, v27
	global_store_dwordx4 v[28:29], v[18:21], off
	s_nop 1
	v_mul_f32_e32 v18, v168, v168
	v_pk_mul_f32 v[10:11], v[4:5], v[18:19] op_sel_hi:[1,0]
	v_pk_mul_f32 v[4:5], v[2:3], v[18:19] op_sel_hi:[1,0]
	v_lshlrev_b64 v[2:3], 11, v[148:149]
	v_lshl_add_u64 v[2:3], s[12:13], 0, v[2:3]
	v_lshl_add_u64 v[2:3], v[2:3], 0, s[2:3]
	v_lshl_add_u64 v[2:3], v[2:3], 0, s[8:9]
	v_lshl_add_u64 v[12:13], v[2:3], 0, v[138:139]
	s_mov_b64 s[2:3], -1
	v_pk_mul_f32 v[8:9], v[8:9], v[18:19] op_sel_hi:[1,0]
	v_pk_mul_f32 v[6:7], v[6:7], v[18:19] op_sel_hi:[1,0]
	s_nop 0
	v_cvt_pk_bf16_f32 v2, v6, v7
	v_cvt_pk_bf16_f32 v3, v8, v9
	v_cvt_pk_bf16_f32 v4, v4, v5
	v_cvt_pk_bf16_f32 v5, v10, v11
	global_store_dwordx4 v[12:13], v[2:5], off
	s_cbranch_vccnz .LBB0_1930
	s_andn2_b64 vcc, exec, s[10:11]
	s_cbranch_vccnz .LBB0_1929
	s_barrier
	s_branch .LBB0_1929

.LBB0_2210:
	v_lshl_add_u32 v162, s26, 8, v1
	s_and_b32 s99, s47, 1
	s_lshl_b32 s99, s99, 12
	s_add_i32 s99, s99, 0x21000
	v_lshl_add_u32 v252, v1, 4, s99
	v_ashrrev_i32_e32 v163, 31, v162
	v_or_b32_e32 v160, 16, v162
	v_lshl_add_u64 v[148:149], v[162:163], 4, s[76:77]
	v_ashrrev_i32_e32 v161, 31, v160
	v_lshl_add_u64 v[150:151], v[160:161], 4, s[76:77]
	ds_read_b128 v[170:173], v252
	ds_read_b128 v[174:177], v252 offset:256
	v_or_b32_e32 v158, 32, v162
	v_ashrrev_i32_e32 v159, 31, v158
	v_or_b32_e32 v156, 48, v162
	v_add_u32_e32 v154, 0x80, v162
	v_lshl_add_u64 v[148:149], v[158:159], 4, s[76:77]
	v_ashrrev_i32_e32 v157, 31, v156
	v_ashrrev_i32_e32 v155, 31, v154
	v_add_u32_e32 v152, 0x90, v162
	v_lshl_add_u64 v[150:151], v[156:157], 4, s[76:77]
	ds_read_b128 v[178:181], v252 offset:512
	ds_read_b128 v[182:185], v252 offset:768
	v_lshl_add_u64 v[148:149], v[154:155], 4, s[76:77]
	v_ashrrev_i32_e32 v153, 31, v152
	v_lshl_add_u64 v[150:151], v[152:153], 4, s[76:77]
	ds_read_b128 v[186:189], v252 offset:2048
	ds_read_b128 v[190:193], v252 offset:2304
	v_add_u32_e32 v150, 0xa0, v162
	v_ashrrev_i32_e32 v151, 31, v150
	v_lshl_add_u64 v[148:149], v[150:151], 4, s[76:77]
	ds_read_b128 v[194:197], v252 offset:2560
	v_add_u32_e32 v148, 0xb0, v162
	v_ashrrev_i32_e32 v149, 31, v148
	v_lshl_add_u64 v[198:199], v[148:149], 4, s[76:77]
	ds_read_b128 v[198:201], v252 offset:2816
	v_pk_mul_f32 v[124:125], v[128:129], v[124:125]
	v_pk_mul_f32 v[122:123], v[126:127], v[122:123]
	v_pk_mul_f32 v[116:117], v[120:121], v[116:117]
	v_pk_mul_f32 v[114:115], v[118:119], v[114:115]
	s_lshl_b32 s2, s48, 7
	s_ashr_i32 s3, s2, 31
	s_lshl_b64 s[2:3], s[2:3], 1
	v_pk_mul_f32 v[108:109], v[112:113], v[108:109]
	v_pk_mul_f32 v[106:107], v[110:111], v[106:107]
	v_pk_mul_f32 v[100:101], v[104:105], v[100:101]
	v_pk_mul_f32 v[98:99], v[102:103], v[98:99]
	v_pk_mul_f32 v[92:93], v[96:97], v[92:93]
	v_pk_mul_f32 v[90:91], v[94:95], v[90:91]
	v_pk_mul_f32 v[84:85], v[88:89], v[84:85]
	v_pk_mul_f32 v[82:83], v[86:87], v[82:83]
	v_pk_mul_f32 v[76:77], v[80:81], v[76:77]
	v_pk_mul_f32 v[74:75], v[78:79], v[74:75]
	v_pk_mul_f32 v[68:69], v[72:73], v[68:69]
	v_pk_mul_f32 v[66:67], v[70:71], v[66:67]
	v_pk_mul_f32 v[60:61], v[64:65], v[60:61]
	v_pk_mul_f32 v[58:59], v[62:63], v[58:59]
	v_pk_mul_f32 v[52:53], v[56:57], v[52:53]
	v_pk_mul_f32 v[50:51], v[54:55], v[50:51]
	v_pk_mul_f32 v[44:45], v[48:49], v[44:45]
	v_pk_mul_f32 v[42:43], v[46:47], v[42:43]
	v_pk_mul_f32 v[36:37], v[40:41], v[36:37]
	v_pk_mul_f32 v[34:35], v[38:39], v[34:35]
	v_pk_mul_f32 v[28:29], v[32:33], v[28:29]
	v_pk_mul_f32 v[26:27], v[30:31], v[26:27]
	v_pk_mul_f32 v[20:21], v[24:25], v[20:21]
	v_pk_mul_f32 v[18:19], v[22:23], v[18:19]
	v_pk_mul_f32 v[12:13], v[16:17], v[12:13]
	v_pk_mul_f32 v[10:11], v[14:15], v[10:11]
	v_pk_mul_f32 v[4:5], v[8:9], v[4:5]
	v_pk_mul_f32 v[2:3], v[6:7], v[2:3]
	s_andn2_b64 vcc, exec, s[4:5]
	s_waitcnt lgkmcnt(0)
	v_mov_b32_e32 v202, v171
	v_mov_b32_e32 v203, v172
	v_mov_b32_e32 v171, v173
	v_pk_add_f32 v[170:171], v[202:203], v[170:171]
	v_mov_b32_e32 v172, v175
	v_add_f32_e32 v149, v170, v171
	v_fmamk_f32 v149, v149, 0x3a800000, v168
	v_rsq_f32_e32 v169, v149
	v_mov_b32_e32 v173, v176
	v_mov_b32_e32 v175, v177
	v_mov_b32_e32 v176, v179
	v_mov_b32_e32 v177, v180
	v_mov_b32_e32 v179, v181
	v_mov_b32_e32 v180, v183
	v_mov_b32_e32 v181, v184
	v_mov_b32_e32 v183, v185
	v_mov_b32_e32 v184, v187
	v_mov_b32_e32 v185, v188
	v_mov_b32_e32 v187, v189
	v_pk_add_f32 v[170:171], v[172:173], v[174:175]
	v_pk_add_f32 v[172:173], v[176:177], v[178:179]
	v_pk_add_f32 v[174:175], v[180:181], v[182:183]
	v_pk_add_f32 v[176:177], v[184:185], v[186:187]
	v_add_f32_e32 v153, v172, v173
	v_mul_f32_e32 v172, 0xbfb8aa3b, v169
	v_add_f32_e32 v155, v174, v175
	v_add_f32_e32 v157, v176, v177
	v_pk_mul_f32 v[174:175], v[128:129], v[172:173] op_sel_hi:[1,0]
	v_pk_mul_f32 v[176:177], v[126:127], v[172:173] op_sel_hi:[1,0]
	v_exp_f32_e32 v174, v174
	v_exp_f32_e32 v176, v176
	v_exp_f32_e32 v175, v175
	v_exp_f32_e32 v177, v177
	v_add_f32_e32 v151, v170, v171
	v_fmamk_f32 v149, v151, 0x3a800000, v168
	v_fmamk_f32 v151, v153, 0x3a800000, v168
	v_rsq_f32_e32 v171, v151
	v_pk_add_f32 v[126:127], v[174:175], 1.0 op_sel_hi:[1,0]
	v_pk_add_f32 v[128:129], v[176:177], 1.0 op_sel_hi:[1,0]
	v_rcp_f32_e32 v126, v126
	v_rcp_f32_e32 v128, v128
	v_rcp_f32_e32 v127, v127
	v_rcp_f32_e32 v129, v129
	v_mul_f32_e32 v170, v169, v169
	v_pk_mul_f32 v[122:123], v[122:123], v[170:171] op_sel_hi:[1,0]
	v_pk_mul_f32 v[124:125], v[124:125], v[170:171] op_sel_hi:[1,0]
	v_pk_mul_f32 v[122:123], v[122:123], v[128:129]
	v_pk_mul_f32 v[124:125], v[124:125], v[126:127]
	v_pk_mul_f32 v[126:127], v[120:121], v[172:173] op_sel_hi:[1,0]
	v_pk_mul_f32 v[128:129], v[118:119], v[172:173] op_sel_hi:[1,0]
	v_exp_f32_e32 v126, v126
	v_exp_f32_e32 v128, v128
	v_exp_f32_e32 v127, v127
	v_exp_f32_e32 v129, v129
	v_mov_b32_e32 v188, v191
	v_mov_b32_e32 v189, v192
	v_pk_add_f32 v[118:119], v[126:127], 1.0 op_sel_hi:[1,0]
	v_pk_add_f32 v[120:121], v[128:129], 1.0 op_sel_hi:[1,0]
	v_rcp_f32_e32 v118, v118
	v_rcp_f32_e32 v120, v120
	v_rcp_f32_e32 v119, v119
	v_rcp_f32_e32 v121, v121
	v_mov_b32_e32 v191, v193
	v_mov_b32_e32 v192, v195
	v_mov_b32_e32 v193, v196
	v_mov_b32_e32 v195, v197
	v_mov_b32_e32 v196, v199
	v_mov_b32_e32 v197, v200
	v_mov_b32_e32 v199, v201
	v_pk_add_f32 v[178:179], v[188:189], v[190:191]
	v_pk_add_f32 v[180:181], v[192:193], v[194:195]
	v_pk_add_f32 v[182:183], v[196:197], v[198:199]
	v_pk_mul_f32 v[114:115], v[114:115], v[170:171] op_sel_hi:[1,0]
	v_pk_mul_f32 v[116:117], v[116:117], v[170:171] op_sel_hi:[1,0]
	v_add_f32_e32 v159, v178, v179
	v_add_f32_e32 v161, v180, v181
	v_add_f32_e32 v163, v182, v183
	v_pk_mul_f32 v[126:127], v[116:117], v[118:119]
	v_pk_mul_f32 v[118:119], v[114:115], v[120:121]
	v_mov_b64_e32 v[114:115], s[12:13]
	v_fmamk_f32 v153, v155, 0x3a800000, v168
	v_fmamk_f32 v155, v157, 0x3a800000, v168
	v_fmamk_f32 v157, v159, 0x3a800000, v168
	v_fmamk_f32 v159, v161, 0x3a800000, v168
	v_fmamk_f32 v161, v163, 0x3a800000, v168
	v_rsq_f32_e32 v163, v149
	v_mad_i64_i32 v[116:117], s[0:1], v162, s46, v[114:115]
	v_lshl_add_u64 v[116:117], v[116:117], 0, s[2:3]
	v_lshl_add_u64 v[116:117], v[116:117], 0, s[8:9]
	v_lshl_add_u64 v[120:121], v[116:117], 0, v[138:139]
	v_cvt_pk_bf16_f32 v116, v122, v123
	v_cvt_pk_bf16_f32 v117, v124, v125
	v_cvt_pk_bf16_f32 v118, v118, v119
	v_cvt_pk_bf16_f32 v119, v126, v127
	global_store_dwordx4 v[120:121], v[116:119], off
	v_rsq_f32_e32 v153, v153
	v_rsq_f32_e32 v155, v155
	v_mul_f32_e32 v118, 0xbfb8aa3b, v163
	v_pk_mul_f32 v[120:121], v[112:113], v[118:119] op_sel_hi:[1,0]
	v_pk_mul_f32 v[122:123], v[110:111], v[118:119] op_sel_hi:[1,0]
	v_exp_f32_e32 v120, v120
	v_exp_f32_e32 v122, v122
	v_exp_f32_e32 v121, v121
	v_exp_f32_e32 v123, v123
	v_mul_f32_e32 v116, v163, v163
	v_pk_mul_f32 v[106:107], v[106:107], v[116:117] op_sel_hi:[1,0]
	v_pk_add_f32 v[110:111], v[120:121], 1.0 op_sel_hi:[1,0]
	v_pk_add_f32 v[112:113], v[122:123], 1.0 op_sel_hi:[1,0]
	v_rcp_f32_e32 v110, v110
	v_rcp_f32_e32 v112, v112
	v_rcp_f32_e32 v111, v111
	v_rcp_f32_e32 v113, v113
	v_pk_mul_f32 v[108:109], v[108:109], v[116:117] op_sel_hi:[1,0]
	v_pk_mul_f32 v[98:99], v[98:99], v[116:117] op_sel_hi:[1,0]
	v_pk_mul_f32 v[108:109], v[108:109], v[110:111]
	v_pk_mul_f32 v[106:107], v[106:107], v[112:113]
	v_pk_mul_f32 v[110:111], v[104:105], v[118:119] op_sel_hi:[1,0]
	v_pk_mul_f32 v[112:113], v[102:103], v[118:119] op_sel_hi:[1,0]
	v_exp_f32_e32 v110, v110
	v_exp_f32_e32 v112, v112
	v_exp_f32_e32 v111, v111
	v_exp_f32_e32 v113, v113
	v_pk_mul_f32 v[100:101], v[100:101], v[116:117] op_sel_hi:[1,0]
	v_rsq_f32_e32 v157, v157
	v_pk_add_f32 v[102:103], v[110:111], 1.0 op_sel_hi:[1,0]
	v_pk_add_f32 v[104:105], v[112:113], 1.0 op_sel_hi:[1,0]
	v_rcp_f32_e32 v102, v102
	v_rcp_f32_e32 v104, v104
	v_rcp_f32_e32 v103, v103
	v_rcp_f32_e32 v105, v105
	v_rsq_f32_e32 v151, v159
	v_rsq_f32_e32 v149, v161
	v_pk_mul_f32 v[102:103], v[100:101], v[102:103]
	v_pk_mul_f32 v[100:101], v[98:99], v[104:105]
	v_mad_i64_i32 v[98:99], s[0:1], v160, s46, v[114:115]
	v_lshl_add_u64 v[98:99], v[98:99], 0, s[2:3]
	v_lshl_add_u64 v[98:99], v[98:99], 0, s[8:9]
	v_lshl_add_u64 v[104:105], v[98:99], 0, v[138:139]
	v_cvt_pk_bf16_f32 v98, v106, v107
	v_cvt_pk_bf16_f32 v99, v108, v109
	v_cvt_pk_bf16_f32 v100, v100, v101
	v_cvt_pk_bf16_f32 v101, v102, v103
	global_store_dwordx4 v[104:105], v[98:101], off
	s_nop 1
	v_mul_f32_e32 v100, 0xbfb8aa3b, v171
	v_pk_mul_f32 v[102:103], v[96:97], v[100:101] op_sel_hi:[1,0]
	v_pk_mul_f32 v[104:105], v[94:95], v[100:101] op_sel_hi:[1,0]
	v_exp_f32_e32 v102, v102
	v_exp_f32_e32 v104, v104
	v_exp_f32_e32 v103, v103
	v_exp_f32_e32 v105, v105
	v_mul_f32_e32 v98, v171, v171
	v_pk_mul_f32 v[90:91], v[90:91], v[98:99] op_sel_hi:[1,0]
	v_pk_add_f32 v[94:95], v[102:103], 1.0 op_sel_hi:[1,0]
	v_pk_add_f32 v[96:97], v[104:105], 1.0 op_sel_hi:[1,0]
	v_rcp_f32_e32 v94, v94
	v_rcp_f32_e32 v96, v96
	v_rcp_f32_e32 v95, v95
	v_rcp_f32_e32 v97, v97
	v_pk_mul_f32 v[92:93], v[92:93], v[98:99] op_sel_hi:[1,0]
	v_pk_mul_f32 v[82:83], v[82:83], v[98:99] op_sel_hi:[1,0]
	v_pk_mul_f32 v[92:93], v[92:93], v[94:95]
	v_pk_mul_f32 v[90:91], v[90:91], v[96:97]
	v_pk_mul_f32 v[94:95], v[88:89], v[100:101] op_sel_hi:[1,0]
	v_pk_mul_f32 v[96:97], v[86:87], v[100:101] op_sel_hi:[1,0]
	v_exp_f32_e32 v94, v94
	v_exp_f32_e32 v96, v96
	v_exp_f32_e32 v95, v95
	v_exp_f32_e32 v97, v97
	v_pk_mul_f32 v[84:85], v[84:85], v[98:99] op_sel_hi:[1,0]
	v_pk_add_f32 v[86:87], v[94:95], 1.0 op_sel_hi:[1,0]
	v_pk_add_f32 v[88:89], v[96:97], 1.0 op_sel_hi:[1,0]
	v_rcp_f32_e32 v86, v86
	v_rcp_f32_e32 v88, v88
	v_rcp_f32_e32 v87, v87
	v_rcp_f32_e32 v89, v89
	v_pk_mul_f32 v[86:87], v[84:85], v[86:87]
	v_pk_mul_f32 v[84:85], v[82:83], v[88:89]
	v_mad_i64_i32 v[82:83], s[0:1], v158, s46, v[114:115]
	v_lshl_add_u64 v[82:83], v[82:83], 0, s[2:3]
	v_lshl_add_u64 v[82:83], v[82:83], 0, s[8:9]
	v_lshl_add_u64 v[88:89], v[82:83], 0, v[138:139]
	v_cvt_pk_bf16_f32 v82, v90, v91
	v_cvt_pk_bf16_f32 v83, v92, v93
	v_cvt_pk_bf16_f32 v84, v84, v85
	v_cvt_pk_bf16_f32 v85, v86, v87
	global_store_dwordx4 v[88:89], v[82:85], off
	s_nop 1
	v_mul_f32_e32 v84, 0xbfb8aa3b, v153
	v_pk_mul_f32 v[86:87], v[80:81], v[84:85] op_sel_hi:[1,0]
	v_pk_mul_f32 v[88:89], v[78:79], v[84:85] op_sel_hi:[1,0]
	v_exp_f32_e32 v86, v86
	v_exp_f32_e32 v88, v88
	v_exp_f32_e32 v87, v87
	v_exp_f32_e32 v89, v89
	v_mul_f32_e32 v82, v153, v153
	v_pk_mul_f32 v[74:75], v[74:75], v[82:83] op_sel_hi:[1,0]
	v_pk_add_f32 v[78:79], v[86:87], 1.0 op_sel_hi:[1,0]
	v_pk_add_f32 v[80:81], v[88:89], 1.0 op_sel_hi:[1,0]
	v_rcp_f32_e32 v78, v78
	v_rcp_f32_e32 v80, v80
	v_rcp_f32_e32 v79, v79
	v_rcp_f32_e32 v81, v81
	v_pk_mul_f32 v[76:77], v[76:77], v[82:83] op_sel_hi:[1,0]
	v_pk_mul_f32 v[66:67], v[66:67], v[82:83] op_sel_hi:[1,0]
	v_pk_mul_f32 v[76:77], v[76:77], v[78:79]
	v_pk_mul_f32 v[74:75], v[74:75], v[80:81]
	v_pk_mul_f32 v[78:79], v[72:73], v[84:85] op_sel_hi:[1,0]
	v_pk_mul_f32 v[80:81], v[70:71], v[84:85] op_sel_hi:[1,0]
	v_exp_f32_e32 v78, v78
	v_exp_f32_e32 v80, v80
	v_exp_f32_e32 v79, v79
	v_exp_f32_e32 v81, v81
	v_pk_mul_f32 v[68:69], v[68:69], v[82:83] op_sel_hi:[1,0]
	v_pk_add_f32 v[70:71], v[78:79], 1.0 op_sel_hi:[1,0]
	v_pk_add_f32 v[72:73], v[80:81], 1.0 op_sel_hi:[1,0]
	v_rcp_f32_e32 v70, v70
	v_rcp_f32_e32 v72, v72
	v_rcp_f32_e32 v71, v71
	v_rcp_f32_e32 v73, v73
	v_pk_mul_f32 v[70:71], v[68:69], v[70:71]
	v_pk_mul_f32 v[68:69], v[66:67], v[72:73]
	v_mad_i64_i32 v[66:67], s[0:1], v156, s46, v[114:115]
	v_lshl_add_u64 v[66:67], v[66:67], 0, s[2:3]
	v_lshl_add_u64 v[66:67], v[66:67], 0, s[8:9]
	v_lshl_add_u64 v[72:73], v[66:67], 0, v[138:139]
	v_cvt_pk_bf16_f32 v66, v74, v75
	v_cvt_pk_bf16_f32 v67, v76, v77
	v_cvt_pk_bf16_f32 v68, v68, v69
	v_cvt_pk_bf16_f32 v69, v70, v71
	global_store_dwordx4 v[72:73], v[66:69], off
	s_nop 1
	v_mul_f32_e32 v68, 0xbfb8aa3b, v155
	v_pk_mul_f32 v[70:71], v[64:65], v[68:69] op_sel_hi:[1,0]
	v_pk_mul_f32 v[72:73], v[62:63], v[68:69] op_sel_hi:[1,0]
	v_exp_f32_e32 v70, v70
	v_exp_f32_e32 v72, v72
	v_exp_f32_e32 v71, v71
	v_exp_f32_e32 v73, v73
	v_mul_f32_e32 v66, v155, v155
	v_pk_mul_f32 v[58:59], v[58:59], v[66:67] op_sel_hi:[1,0]
	v_pk_add_f32 v[62:63], v[70:71], 1.0 op_sel_hi:[1,0]
	v_pk_add_f32 v[64:65], v[72:73], 1.0 op_sel_hi:[1,0]
	v_rcp_f32_e32 v62, v62
	v_rcp_f32_e32 v64, v64
	v_rcp_f32_e32 v63, v63
	v_rcp_f32_e32 v65, v65
	v_pk_mul_f32 v[60:61], v[60:61], v[66:67] op_sel_hi:[1,0]
	v_pk_mul_f32 v[50:51], v[50:51], v[66:67] op_sel_hi:[1,0]
	v_pk_mul_f32 v[60:61], v[60:61], v[62:63]
	v_pk_mul_f32 v[58:59], v[58:59], v[64:65]
	v_pk_mul_f32 v[62:63], v[56:57], v[68:69] op_sel_hi:[1,0]
	v_pk_mul_f32 v[64:65], v[54:55], v[68:69] op_sel_hi:[1,0]
	v_exp_f32_e32 v62, v62
	v_exp_f32_e32 v64, v64
	v_exp_f32_e32 v63, v63
	v_exp_f32_e32 v65, v65
	v_pk_mul_f32 v[52:53], v[52:53], v[66:67] op_sel_hi:[1,0]
	v_pk_add_f32 v[54:55], v[62:63], 1.0 op_sel_hi:[1,0]
	v_pk_add_f32 v[56:57], v[64:65], 1.0 op_sel_hi:[1,0]
	v_rcp_f32_e32 v54, v54
	v_rcp_f32_e32 v56, v56
	v_rcp_f32_e32 v55, v55
	v_rcp_f32_e32 v57, v57
	v_pk_mul_f32 v[54:55], v[52:53], v[54:55]
	v_pk_mul_f32 v[52:53], v[50:51], v[56:57]
	v_mad_i64_i32 v[50:51], s[0:1], v154, s46, v[114:115]
	v_lshl_add_u64 v[50:51], v[50:51], 0, s[2:3]
	v_lshl_add_u64 v[50:51], v[50:51], 0, s[8:9]
	v_lshl_add_u64 v[56:57], v[50:51], 0, v[138:139]
	v_cvt_pk_bf16_f32 v50, v58, v59
	v_cvt_pk_bf16_f32 v51, v60, v61
	v_cvt_pk_bf16_f32 v52, v52, v53
	v_cvt_pk_bf16_f32 v53, v54, v55
	global_store_dwordx4 v[56:57], v[50:53], off
	s_nop 1
	v_mul_f32_e32 v52, 0xbfb8aa3b, v157
	v_pk_mul_f32 v[54:55], v[48:49], v[52:53] op_sel_hi:[1,0]
	v_pk_mul_f32 v[56:57], v[46:47], v[52:53] op_sel_hi:[1,0]
	v_exp_f32_e32 v54, v54
	v_exp_f32_e32 v56, v56
	v_exp_f32_e32 v55, v55
	v_exp_f32_e32 v57, v57
	v_mul_f32_e32 v50, v157, v157
	v_pk_mul_f32 v[42:43], v[42:43], v[50:51] op_sel_hi:[1,0]
	v_pk_add_f32 v[46:47], v[54:55], 1.0 op_sel_hi:[1,0]
	v_pk_add_f32 v[48:49], v[56:57], 1.0 op_sel_hi:[1,0]
	v_rcp_f32_e32 v46, v46
	v_rcp_f32_e32 v48, v48
	v_rcp_f32_e32 v47, v47
	v_rcp_f32_e32 v49, v49
	v_pk_mul_f32 v[44:45], v[44:45], v[50:51] op_sel_hi:[1,0]
	v_pk_mul_f32 v[34:35], v[34:35], v[50:51] op_sel_hi:[1,0]
	v_pk_mul_f32 v[44:45], v[44:45], v[46:47]
	v_pk_mul_f32 v[42:43], v[42:43], v[48:49]
	v_pk_mul_f32 v[46:47], v[40:41], v[52:53] op_sel_hi:[1,0]
	v_pk_mul_f32 v[48:49], v[38:39], v[52:53] op_sel_hi:[1,0]
	v_exp_f32_e32 v46, v46
	v_exp_f32_e32 v48, v48
	v_exp_f32_e32 v47, v47
	v_exp_f32_e32 v49, v49
	v_pk_mul_f32 v[36:37], v[36:37], v[50:51] op_sel_hi:[1,0]
	v_pk_add_f32 v[38:39], v[46:47], 1.0 op_sel_hi:[1,0]
	v_pk_add_f32 v[40:41], v[48:49], 1.0 op_sel_hi:[1,0]
	v_rcp_f32_e32 v38, v38
	v_rcp_f32_e32 v40, v40
	v_rcp_f32_e32 v39, v39
	v_rcp_f32_e32 v41, v41
	v_pk_mul_f32 v[38:39], v[36:37], v[38:39]
	v_pk_mul_f32 v[36:37], v[34:35], v[40:41]
	v_mad_i64_i32 v[34:35], s[0:1], v152, s46, v[114:115]
	v_lshl_add_u64 v[34:35], v[34:35], 0, s[2:3]
	v_lshl_add_u64 v[34:35], v[34:35], 0, s[8:9]
	v_lshl_add_u64 v[40:41], v[34:35], 0, v[138:139]
	v_cvt_pk_bf16_f32 v34, v42, v43
	v_cvt_pk_bf16_f32 v35, v44, v45
	v_cvt_pk_bf16_f32 v36, v36, v37
	v_cvt_pk_bf16_f32 v37, v38, v39
	global_store_dwordx4 v[40:41], v[34:37], off
	s_nop 1
	v_mul_f32_e32 v36, 0xbfb8aa3b, v151
	v_pk_mul_f32 v[38:39], v[32:33], v[36:37] op_sel_hi:[1,0]
	v_pk_mul_f32 v[40:41], v[30:31], v[36:37] op_sel_hi:[1,0]
	v_exp_f32_e32 v38, v38
	v_exp_f32_e32 v40, v40
	v_exp_f32_e32 v39, v39
	v_exp_f32_e32 v41, v41
	v_mul_f32_e32 v34, v151, v151
	v_pk_mul_f32 v[26:27], v[26:27], v[34:35] op_sel_hi:[1,0]
	v_pk_add_f32 v[30:31], v[38:39], 1.0 op_sel_hi:[1,0]
	v_pk_add_f32 v[32:33], v[40:41], 1.0 op_sel_hi:[1,0]
	v_rcp_f32_e32 v30, v30
	v_rcp_f32_e32 v32, v32
	v_rcp_f32_e32 v31, v31
	v_rcp_f32_e32 v33, v33
	v_pk_mul_f32 v[28:29], v[28:29], v[34:35] op_sel_hi:[1,0]
	v_pk_mul_f32 v[18:19], v[18:19], v[34:35] op_sel_hi:[1,0]
	v_pk_mul_f32 v[28:29], v[28:29], v[30:31]
	v_pk_mul_f32 v[26:27], v[26:27], v[32:33]
	v_pk_mul_f32 v[30:31], v[24:25], v[36:37] op_sel_hi:[1,0]
	v_pk_mul_f32 v[32:33], v[22:23], v[36:37] op_sel_hi:[1,0]
	v_exp_f32_e32 v30, v30
	v_exp_f32_e32 v32, v32
	v_exp_f32_e32 v31, v31
	v_exp_f32_e32 v33, v33
	v_pk_mul_f32 v[20:21], v[20:21], v[34:35] op_sel_hi:[1,0]
	v_pk_add_f32 v[22:23], v[30:31], 1.0 op_sel_hi:[1,0]
	v_pk_add_f32 v[24:25], v[32:33], 1.0 op_sel_hi:[1,0]
	v_rcp_f32_e32 v22, v22
	v_rcp_f32_e32 v24, v24
	v_rcp_f32_e32 v23, v23
	v_rcp_f32_e32 v25, v25
	v_pk_mul_f32 v[22:23], v[20:21], v[22:23]
	v_pk_mul_f32 v[20:21], v[18:19], v[24:25]
	v_mad_i64_i32 v[18:19], s[0:1], v150, s46, v[114:115]
	v_lshl_add_u64 v[18:19], v[18:19], 0, s[2:3]
	v_lshl_add_u64 v[18:19], v[18:19], 0, s[8:9]
	v_lshl_add_u64 v[24:25], v[18:19], 0, v[138:139]
	v_cvt_pk_bf16_f32 v18, v26, v27
	v_cvt_pk_bf16_f32 v19, v28, v29
	v_cvt_pk_bf16_f32 v20, v20, v21
	v_cvt_pk_bf16_f32 v21, v22, v23
	global_store_dwordx4 v[24:25], v[18:21], off
	s_nop 1
	v_mul_f32_e32 v20, 0xbfb8aa3b, v149
	v_pk_mul_f32 v[22:23], v[16:17], v[20:21] op_sel_hi:[1,0]
	v_pk_mul_f32 v[24:25], v[14:15], v[20:21] op_sel_hi:[1,0]
	v_exp_f32_e32 v22, v22
	v_exp_f32_e32 v24, v24
	v_exp_f32_e32 v23, v23
	v_exp_f32_e32 v25, v25
	v_mul_f32_e32 v18, v149, v149
	v_pk_mul_f32 v[10:11], v[10:11], v[18:19] op_sel_hi:[1,0]
	v_pk_add_f32 v[14:15], v[22:23], 1.0 op_sel_hi:[1,0]
	v_pk_add_f32 v[16:17], v[24:25], 1.0 op_sel_hi:[1,0]
	v_rcp_f32_e32 v14, v14
	v_rcp_f32_e32 v16, v16
	v_rcp_f32_e32 v15, v15
	v_rcp_f32_e32 v17, v17
	v_pk_mul_f32 v[12:13], v[12:13], v[18:19] op_sel_hi:[1,0]
	v_pk_mul_f32 v[2:3], v[2:3], v[18:19] op_sel_hi:[1,0]
	v_pk_mul_f32 v[12:13], v[12:13], v[14:15]
	v_pk_mul_f32 v[10:11], v[10:11], v[16:17]
	v_pk_mul_f32 v[14:15], v[8:9], v[20:21] op_sel_hi:[1,0]
	v_pk_mul_f32 v[16:17], v[6:7], v[20:21] op_sel_hi:[1,0]
	v_exp_f32_e32 v14, v14
	v_exp_f32_e32 v16, v16
	v_exp_f32_e32 v15, v15
	v_exp_f32_e32 v17, v17
	v_pk_mul_f32 v[4:5], v[4:5], v[18:19] op_sel_hi:[1,0]
	v_pk_add_f32 v[6:7], v[14:15], 1.0 op_sel_hi:[1,0]
	v_pk_add_f32 v[8:9], v[16:17], 1.0 op_sel_hi:[1,0]
	v_rcp_f32_e32 v6, v6
	v_rcp_f32_e32 v8, v8
	v_rcp_f32_e32 v7, v7
	v_rcp_f32_e32 v9, v9
	v_pk_mul_f32 v[6:7], v[4:5], v[6:7]
	v_pk_mul_f32 v[4:5], v[2:3], v[8:9]
	v_mad_i64_i32 v[2:3], s[0:1], v148, s46, v[114:115]
	v_lshl_add_u64 v[2:3], v[2:3], 0, s[2:3]
	v_lshl_add_u64 v[2:3], v[2:3], 0, s[8:9]
	v_lshl_add_u64 v[8:9], v[2:3], 0, v[138:139]
	s_mov_b64 s[2:3], -1
	v_cvt_pk_bf16_f32 v2, v10, v11
	v_cvt_pk_bf16_f32 v3, v12, v13
	v_cvt_pk_bf16_f32 v4, v4, v5
	v_cvt_pk_bf16_f32 v5, v6, v7
	global_store_dwordx4 v[8:9], v[2:5], off
	s_cbranch_vccnz .LBB0_2203
	s_andn2_b64 vcc, exec, s[10:11]
	s_cbranch_vccnz .LBB0_2202
	s_barrier
	s_branch .LBB0_2202

	.amdhsa_kernel _Z8mega_fwd4Args
		.amdhsa_group_segment_fixed_size 0
		.amdhsa_private_segment_fixed_size 0
		.amdhsa_kernarg_size 448
		.amdhsa_user_sgpr_count 2
		.amdhsa_user_sgpr_dispatch_ptr 0
		.amdhsa_user_sgpr_queue_ptr 0
		.amdhsa_user_sgpr_kernarg_segment_ptr 1
		.amdhsa_user_sgpr_dispatch_id 0
		.amdhsa_user_sgpr_kernarg_preload_length 0
		.amdhsa_user_sgpr_kernarg_preload_offset 0
		.amdhsa_user_sgpr_private_segment_size 0
		.amdhsa_uses_dynamic_stack 0
		.amdhsa_enable_private_segment 0
		.amdhsa_system_sgpr_workgroup_id_x 1
		.amdhsa_system_sgpr_workgroup_id_y 0
		.amdhsa_system_sgpr_workgroup_id_z 0
		.amdhsa_system_sgpr_workgroup_info 0
		.amdhsa_system_vgpr_workitem_id 0
		.amdhsa_next_free_vgpr 256
		.amdhsa_next_free_sgpr 102
		.amdhsa_accum_offset 256
		.amdhsa_reserve_vcc 1
		.amdhsa_float_round_mode_32 0
		.amdhsa_float_round_mode_16_64 0
		.amdhsa_float_denorm_mode_32 3
		.amdhsa_float_denorm_mode_16_64 3
		.amdhsa_dx10_clamp 1
		.amdhsa_ieee_mode 1
		.amdhsa_fp16_overflow 0
		.amdhsa_tg_split 0
		.amdhsa_exception_fp_ieee_invalid_op 0
		.amdhsa_exception_fp_denorm_src 0
		.amdhsa_exception_fp_ieee_div_zero 0
		.amdhsa_exception_fp_ieee_overflow 0
		.amdhsa_exception_fp_ieee_underflow 0
		.amdhsa_exception_fp_ieee_inexact 0
		.amdhsa_exception_int_div_zero 0
	.end_amdhsa_kernel

amdhsa.kernels:
  - .agpr_count:     0
    .args:
      - .offset:         0
        .size:           192
        .value_kind:     by_value
      - .offset:         192
        .size:           4
        .value_kind:     hidden_block_count_x
      - .offset:         196
        .size:           4
        .value_kind:     hidden_block_count_y
      - .offset:         200
        .size:           4
        .value_kind:     hidden_block_count_z
      - .offset:         204
        .size:           2
        .value_kind:     hidden_group_size_x
      - .offset:         206
        .size:           2
        .value_kind:     hidden_group_size_y
      - .offset:         208
        .size:           2
        .value_kind:     hidden_group_size_z
      - .offset:         210
        .size:           2
        .value_kind:     hidden_remainder_x
      - .offset:         212
        .size:           2
        .value_kind:     hidden_remainder_y
      - .offset:         214
        .size:           2
        .value_kind:     hidden_remainder_z
      - .offset:         232
        .size:           8
        .value_kind:     hidden_global_offset_x
      - .offset:         240
        .size:           8
        .value_kind:     hidden_global_offset_y
      - .offset:         248
        .size:           8
        .value_kind:     hidden_global_offset_z
      - .offset:         256
        .size:           2
        .value_kind:     hidden_grid_dims
      - .offset:         312
        .size:           4
        .value_kind:     hidden_dynamic_lds_size
    .group_segment_fixed_size: 0
    .kernarg_segment_align: 8
    .kernarg_segment_size: 448
    .language:       OpenCL C
    .language_version:
      - 2
      - 0
    .max_flat_workgroup_size: 512
    .name:           _Z8mega_fwd4Args
    .private_segment_fixed_size: 0
    .sgpr_count:     108
    .sgpr_spill_count: 123
    .symbol:         _Z8mega_fwd4Args.kd
    .uniform_work_group_size: 1
    .uses_dynamic_stack: false
    .vgpr_count:     256
    .vgpr_spill_count: 0
    .wavefront_size: 64
